# GEMM K loops: s_nop fillers between m0 writes and LDS-DMA loads replaced by real work (pointer adds or the phase's last ds_read); 8 of 10 nops per iteration gone
# baseline (speedup 1.0000x reference)
.LBB0_118:
	ds_read_b128 v[128:131], v221
	ds_read_b128 v[132:135], v221 offset:1024
	ds_read_b128 v[136:139], v221 offset:2048
	ds_read_b128 v[140:143], v221 offset:3072
	s_add_u32 s8, s6, 0xfff80080
	s_addc_u32 s9, s7, -1
	s_cmp_eq_u32 s53, 28
	s_cselect_b32 s11, s5, s9
	s_cselect_b32 s10, s33, s8
	s_cselect_b32 s9, s43, s52
	s_cselect_b32 s8, s45, s51

	s_add_i32 m0, s58, 0xc000
	ds_read_b128 v[144:147], v222
	ds_read_b128 v[148:151], v222 offset:1024
	ds_read_b128 v[152:155], v222 offset:2048
	ds_read_b128 v[156:159], v222 offset:3072
	ds_read_b128 v[160:163], v222 offset:4096
	ds_read_b128 v[164:167], v222 offset:5120
	ds_read_b128 v[190:193], v222 offset:6144

	global_load_lds_dwordx4 v182, s[6:7]
	s_add_i32 m0, s58, 0xe000
	ds_read_b128 v[194:197], v222 offset:7168

	global_load_lds_dwordx4 v184, s[6:7]
	s_waitcnt lgkmcnt(8)
	s_barrier
	s_waitcnt lgkmcnt(0)


	v_mfma_f32_16x16x32_bf16 v[124:127], v[128:131], v[144:147], v[124:127]
	v_mfma_f32_16x16x32_bf16 v[116:119], v[136:139], v[144:147], v[116:119]
	v_mfma_f32_16x16x32_bf16 v[108:111], v[128:131], v[152:155], v[108:111]
	v_mfma_f32_16x16x32_bf16 v[100:103], v[136:139], v[152:155], v[100:103]
	v_mfma_f32_16x16x32_bf16 v[92:95], v[128:131], v[160:163], v[92:95]
	v_mfma_f32_16x16x32_bf16 v[84:87], v[136:139], v[160:163], v[84:87]
	v_mfma_f32_16x16x32_bf16 v[76:79], v[128:131], v[190:193], v[76:79]
	v_mfma_f32_16x16x32_bf16 v[68:71], v[136:139], v[190:193], v[68:71]
	v_mfma_f32_16x16x32_bf16 v[124:127], v[132:135], v[148:151], v[124:127]
	v_mfma_f32_16x16x32_bf16 v[116:119], v[140:143], v[148:151], v[116:119]
	v_mfma_f32_16x16x32_bf16 v[108:111], v[132:135], v[156:159], v[108:111]
	v_mfma_f32_16x16x32_bf16 v[100:103], v[140:143], v[156:159], v[100:103]
	v_mfma_f32_16x16x32_bf16 v[92:95], v[132:135], v[164:167], v[92:95]
	v_mfma_f32_16x16x32_bf16 v[84:87], v[140:143], v[164:167], v[84:87]
	v_mfma_f32_16x16x32_bf16 v[76:79], v[132:135], v[194:197], v[76:79]
	v_mfma_f32_16x16x32_bf16 v[68:71], v[140:143], v[194:197], v[68:71]

	s_barrier
	s_add_i32 s54, s81, s57
	s_add_u32 s66, s8, s20
	s_addc_u32 s67, s9, s21
	s_mov_b32 m0, s54
	ds_read_b128 v[198:201], v223
	ds_read_b128 v[202:205], v223 offset:1024
	ds_read_b128 v[206:209], v223 offset:2048

	global_load_lds_dwordx4 v172, s[8:9]
	s_add_i32 m0, s54, 0x2000
	ds_read_b128 v[226:229], v223 offset:3072

	global_load_lds_dwordx4 v174, s[8:9]
	s_barrier
	s_waitcnt lgkmcnt(0)


	v_mfma_f32_16x16x32_bf16 v[120:123], v[198:201], v[144:147], v[120:123]
	v_mfma_f32_16x16x32_bf16 v[112:115], v[206:209], v[144:147], v[112:115]
	v_mfma_f32_16x16x32_bf16 v[104:107], v[198:201], v[152:155], v[104:107]
	v_mfma_f32_16x16x32_bf16 v[96:99], v[206:209], v[152:155], v[96:99]
	v_mfma_f32_16x16x32_bf16 v[88:91], v[198:201], v[160:163], v[88:91]
	v_mfma_f32_16x16x32_bf16 v[80:83], v[206:209], v[160:163], v[80:83]
	v_mfma_f32_16x16x32_bf16 v[72:75], v[198:201], v[190:193], v[72:75]
	v_mfma_f32_16x16x32_bf16 v[64:67], v[206:209], v[190:193], v[64:67]
	v_mfma_f32_16x16x32_bf16 v[120:123], v[202:205], v[148:151], v[120:123]
	v_mfma_f32_16x16x32_bf16 v[112:115], v[226:229], v[148:151], v[112:115]
	v_mfma_f32_16x16x32_bf16 v[104:107], v[202:205], v[156:159], v[104:107]
	v_mfma_f32_16x16x32_bf16 v[96:99], v[226:229], v[156:159], v[96:99]
	v_mfma_f32_16x16x32_bf16 v[88:91], v[202:205], v[164:167], v[88:91]
	v_mfma_f32_16x16x32_bf16 v[80:83], v[226:229], v[164:167], v[80:83]
	v_mfma_f32_16x16x32_bf16 v[72:75], v[202:205], v[194:197], v[72:75]
	v_mfma_f32_16x16x32_bf16 v[64:67], v[226:229], v[194:197], v[64:67]

	s_mov_b32 m0, s58
	s_add_u32 s68, s10, s20
	s_addc_u32 s69, s11, s21
	s_barrier
	ds_read_b128 v[144:147], v222 offset:16384
	ds_read_b128 v[148:151], v222 offset:17408
	ds_read_b128 v[152:155], v222 offset:18432
	ds_read_b128 v[156:159], v222 offset:19456
	ds_read_b128 v[160:163], v222 offset:20480
	ds_read_b128 v[164:167], v222 offset:21504
	ds_read_b128 v[190:193], v222 offset:22528

	global_load_lds_dwordx4 v172, s[10:11]
	s_mov_b32 m0, s59
	ds_read_b128 v[194:197], v222 offset:23552

	global_load_lds_dwordx4 v174, s[10:11]
	s_barrier
	s_waitcnt lgkmcnt(0)


	v_mfma_f32_16x16x32_bf16 v[60:63], v[128:131], v[144:147], v[60:63]
	v_mfma_f32_16x16x32_bf16 v[52:55], v[136:139], v[144:147], v[52:55]
	v_mfma_f32_16x16x32_bf16 v[44:47], v[128:131], v[152:155], v[44:47]
	v_mfma_f32_16x16x32_bf16 v[36:39], v[136:139], v[152:155], v[36:39]
	v_mfma_f32_16x16x32_bf16 v[28:31], v[128:131], v[160:163], v[28:31]
	v_mfma_f32_16x16x32_bf16 v[20:23], v[136:139], v[160:163], v[20:23]
	v_mfma_f32_16x16x32_bf16 v[12:15], v[128:131], v[190:193], v[12:15]
	v_mfma_f32_16x16x32_bf16 v[4:7], v[136:139], v[190:193], v[4:7]
	v_mfma_f32_16x16x32_bf16 v[60:63], v[132:135], v[148:151], v[60:63]
	v_mfma_f32_16x16x32_bf16 v[52:55], v[140:143], v[148:151], v[52:55]
	v_mfma_f32_16x16x32_bf16 v[44:47], v[132:135], v[156:159], v[44:47]
	v_mfma_f32_16x16x32_bf16 v[36:39], v[140:143], v[156:159], v[36:39]
	v_mfma_f32_16x16x32_bf16 v[28:31], v[132:135], v[164:167], v[28:31]
	v_mfma_f32_16x16x32_bf16 v[20:23], v[140:143], v[164:167], v[20:23]
	v_mfma_f32_16x16x32_bf16 v[12:15], v[132:135], v[194:197], v[12:15]
	v_mfma_f32_16x16x32_bf16 v[4:7], v[140:143], v[194:197], v[4:7]

	s_barrier
	s_add_u32 s54, s8, 0x80000
	s_addc_u32 s55, s9, 0
	s_add_i32 vcc_lo, s30, s57
	s_mov_b32 m0, vcc_lo
	s_nop 0

	global_load_lds_dwordx4 v172, s[54:55]
	s_add_i32 m0, vcc_lo, 0x2000
	s_nop 0

	global_load_lds_dwordx4 v174, s[54:55]
	s_waitcnt vmcnt(6)
	s_barrier

	v_mfma_f32_16x16x32_bf16 v[56:59], v[198:201], v[144:147], v[56:59]
	v_mfma_f32_16x16x32_bf16 v[48:51], v[206:209], v[144:147], v[48:51]
	v_mfma_f32_16x16x32_bf16 v[40:43], v[198:201], v[152:155], v[40:43]
	v_mfma_f32_16x16x32_bf16 v[32:35], v[206:209], v[152:155], v[32:35]
	v_mfma_f32_16x16x32_bf16 v[24:27], v[198:201], v[160:163], v[24:27]
	v_mfma_f32_16x16x32_bf16 v[16:19], v[206:209], v[160:163], v[16:19]
	v_mfma_f32_16x16x32_bf16 v[8:11], v[198:201], v[190:193], v[8:11]
	v_mfma_f32_16x16x32_bf16 v[0:3], v[206:209], v[190:193], v[0:3]
	v_mfma_f32_16x16x32_bf16 v[56:59], v[202:205], v[148:151], v[56:59]
	v_mfma_f32_16x16x32_bf16 v[48:51], v[226:229], v[148:151], v[48:51]
	v_mfma_f32_16x16x32_bf16 v[40:43], v[202:205], v[156:159], v[40:43]
	v_mfma_f32_16x16x32_bf16 v[32:35], v[226:229], v[156:159], v[32:35]
	v_mfma_f32_16x16x32_bf16 v[24:27], v[202:205], v[164:167], v[24:27]
	v_mfma_f32_16x16x32_bf16 v[16:19], v[226:229], v[164:167], v[16:19]
	v_mfma_f32_16x16x32_bf16 v[8:11], v[202:205], v[194:197], v[8:11]
	v_mfma_f32_16x16x32_bf16 v[0:3], v[226:229], v[194:197], v[0:3]

	s_add_i32 s54, 0, 0x18000
	v_add_u32_e32 v140, s54, v179
	s_barrier
	ds_read_b128 v[128:131], v140
	ds_read_b128 v[132:135], v140 offset:1024
	ds_read_b128 v[136:139], v140 offset:2048
	ds_read_b128 v[140:143], v140 offset:3072
	s_add_u32 s10, s10, 0x80000
	s_addc_u32 s11, s11, 0
	s_mov_b32 m0, s2

	ds_read_b128 v[144:147], v222 offset:32768
	ds_read_b128 v[148:151], v222 offset:33792
	ds_read_b128 v[152:155], v222 offset:34816
	ds_read_b128 v[156:159], v222 offset:35840
	ds_read_b128 v[160:163], v222 offset:36864
	ds_read_b128 v[164:167], v222 offset:37888
	ds_read_b128 v[190:193], v222 offset:38912

	global_load_lds_dwordx4 v172, s[10:11]
	s_mov_b32 m0, s3
	ds_read_b128 v[194:197], v222 offset:39936

	global_load_lds_dwordx4 v174, s[10:11]
	s_waitcnt lgkmcnt(8)
	s_barrier
	s_waitcnt lgkmcnt(0)


	v_mfma_f32_16x16x32_bf16 v[124:127], v[128:131], v[144:147], v[124:127]
	v_mfma_f32_16x16x32_bf16 v[116:119], v[136:139], v[144:147], v[116:119]
	v_mfma_f32_16x16x32_bf16 v[108:111], v[128:131], v[152:155], v[108:111]
	v_mfma_f32_16x16x32_bf16 v[100:103], v[136:139], v[152:155], v[100:103]
	v_mfma_f32_16x16x32_bf16 v[92:95], v[128:131], v[160:163], v[92:95]
	v_mfma_f32_16x16x32_bf16 v[84:87], v[136:139], v[160:163], v[84:87]
	v_mfma_f32_16x16x32_bf16 v[76:79], v[128:131], v[190:193], v[76:79]
	v_mfma_f32_16x16x32_bf16 v[68:71], v[136:139], v[190:193], v[68:71]
	v_mfma_f32_16x16x32_bf16 v[124:127], v[132:135], v[148:151], v[124:127]
	v_mfma_f32_16x16x32_bf16 v[116:119], v[140:143], v[148:151], v[116:119]
	v_mfma_f32_16x16x32_bf16 v[108:111], v[132:135], v[156:159], v[108:111]
	v_mfma_f32_16x16x32_bf16 v[100:103], v[140:143], v[156:159], v[100:103]
	v_mfma_f32_16x16x32_bf16 v[92:95], v[132:135], v[164:167], v[92:95]
	v_mfma_f32_16x16x32_bf16 v[84:87], v[140:143], v[164:167], v[84:87]
	v_mfma_f32_16x16x32_bf16 v[76:79], v[132:135], v[194:197], v[76:79]
	v_mfma_f32_16x16x32_bf16 v[68:71], v[140:143], v[194:197], v[68:71]

	s_barrier
	s_add_i32 s10, 0, 0x1c000
	s_add_i32 s11, s54, s57
	v_add_u32_e32 v180, s10, v179

	s_mov_b32 m0, s11
	ds_read_b128 v[198:201], v180
	ds_read_b128 v[202:205], v180 offset:1024
	ds_read_b128 v[206:209], v180 offset:2048

	global_load_lds_dwordx4 v172, s[66:67]
	s_add_i32 m0, s11, 0x2000
	ds_read_b128 v[226:229], v180 offset:3072

	global_load_lds_dwordx4 v174, s[66:67]
	s_barrier
	s_waitcnt lgkmcnt(0)


	v_mfma_f32_16x16x32_bf16 v[120:123], v[198:201], v[144:147], v[120:123]
	v_mfma_f32_16x16x32_bf16 v[112:115], v[206:209], v[144:147], v[112:115]
	v_mfma_f32_16x16x32_bf16 v[104:107], v[198:201], v[152:155], v[104:107]
	v_mfma_f32_16x16x32_bf16 v[96:99], v[206:209], v[152:155], v[96:99]
	v_mfma_f32_16x16x32_bf16 v[88:91], v[198:201], v[160:163], v[88:91]
	v_mfma_f32_16x16x32_bf16 v[80:83], v[206:209], v[160:163], v[80:83]
	v_mfma_f32_16x16x32_bf16 v[72:75], v[198:201], v[190:193], v[72:75]
	v_mfma_f32_16x16x32_bf16 v[64:67], v[206:209], v[190:193], v[64:67]
	v_mfma_f32_16x16x32_bf16 v[120:123], v[202:205], v[148:151], v[120:123]
	v_mfma_f32_16x16x32_bf16 v[112:115], v[226:229], v[148:151], v[112:115]
	v_mfma_f32_16x16x32_bf16 v[104:107], v[202:205], v[156:159], v[104:107]
	v_mfma_f32_16x16x32_bf16 v[96:99], v[226:229], v[156:159], v[96:99]
	v_mfma_f32_16x16x32_bf16 v[88:91], v[202:205], v[164:167], v[88:91]
	v_mfma_f32_16x16x32_bf16 v[80:83], v[226:229], v[164:167], v[80:83]
	v_mfma_f32_16x16x32_bf16 v[72:75], v[202:205], v[194:197], v[72:75]
	v_mfma_f32_16x16x32_bf16 v[64:67], v[226:229], v[194:197], v[64:67]

	s_mov_b32 m0, s96

	s_barrier
	ds_read_b128 v[144:147], v222 offset:49152
	ds_read_b128 v[148:151], v222 offset:50176
	ds_read_b128 v[152:155], v222 offset:51200
	ds_read_b128 v[156:159], v222 offset:52224
	ds_read_b128 v[160:163], v222 offset:53248
	ds_read_b128 v[164:167], v222 offset:54272
	ds_read_b128 v[190:193], v222 offset:55296

	global_load_lds_dwordx4 v172, s[68:69]
	s_mov_b32 m0, s97
	ds_read_b128 v[194:197], v222 offset:56320

	global_load_lds_dwordx4 v174, s[68:69]
	s_barrier
	s_waitcnt lgkmcnt(0)


	v_mfma_f32_16x16x32_bf16 v[60:63], v[128:131], v[144:147], v[60:63]
	v_mfma_f32_16x16x32_bf16 v[52:55], v[136:139], v[144:147], v[52:55]
	v_mfma_f32_16x16x32_bf16 v[44:47], v[128:131], v[152:155], v[44:47]
	v_mfma_f32_16x16x32_bf16 v[36:39], v[136:139], v[152:155], v[36:39]
	v_mfma_f32_16x16x32_bf16 v[28:31], v[128:131], v[160:163], v[28:31]
	v_mfma_f32_16x16x32_bf16 v[20:23], v[136:139], v[160:163], v[20:23]
	v_mfma_f32_16x16x32_bf16 v[12:15], v[128:131], v[190:193], v[12:15]
	v_mfma_f32_16x16x32_bf16 v[4:7], v[136:139], v[190:193], v[4:7]
	v_mfma_f32_16x16x32_bf16 v[60:63], v[132:135], v[148:151], v[60:63]
	v_mfma_f32_16x16x32_bf16 v[52:55], v[140:143], v[148:151], v[52:55]
	v_mfma_f32_16x16x32_bf16 v[44:47], v[132:135], v[156:159], v[44:47]
	v_mfma_f32_16x16x32_bf16 v[36:39], v[140:143], v[156:159], v[36:39]
	v_mfma_f32_16x16x32_bf16 v[28:31], v[132:135], v[164:167], v[28:31]
	v_mfma_f32_16x16x32_bf16 v[20:23], v[140:143], v[164:167], v[20:23]
	v_mfma_f32_16x16x32_bf16 v[12:15], v[132:135], v[194:197], v[12:15]
	v_mfma_f32_16x16x32_bf16 v[4:7], v[140:143], v[194:197], v[4:7]

	s_barrier
	s_add_i32 s10, s10, s57
	s_mov_b32 m0, s10
	s_add_u32 s8, s8, 0x80080
	s_addc_u32 s9, s9, 0


	global_load_lds_dwordx4 v172, s[8:9]
	s_add_i32 m0, s10, 0x2000
	s_nop 0

	global_load_lds_dwordx4 v174, s[8:9]
	s_waitcnt vmcnt(6)
	s_barrier

	v_mfma_f32_16x16x32_bf16 v[56:59], v[198:201], v[144:147], v[56:59]
	v_mfma_f32_16x16x32_bf16 v[48:51], v[206:209], v[144:147], v[48:51]
	v_mfma_f32_16x16x32_bf16 v[40:43], v[198:201], v[152:155], v[40:43]
	v_mfma_f32_16x16x32_bf16 v[32:35], v[206:209], v[152:155], v[32:35]
	v_mfma_f32_16x16x32_bf16 v[24:27], v[198:201], v[160:163], v[24:27]
	v_mfma_f32_16x16x32_bf16 v[16:19], v[206:209], v[160:163], v[16:19]
	v_mfma_f32_16x16x32_bf16 v[8:11], v[198:201], v[190:193], v[8:11]
	v_mfma_f32_16x16x32_bf16 v[0:3], v[206:209], v[190:193], v[0:3]
	v_mfma_f32_16x16x32_bf16 v[56:59], v[202:205], v[148:151], v[56:59]
	v_mfma_f32_16x16x32_bf16 v[48:51], v[226:229], v[148:151], v[48:51]
	v_mfma_f32_16x16x32_bf16 v[40:43], v[202:205], v[156:159], v[40:43]
	v_mfma_f32_16x16x32_bf16 v[32:35], v[226:229], v[156:159], v[32:35]
	v_mfma_f32_16x16x32_bf16 v[24:27], v[202:205], v[164:167], v[24:27]
	v_mfma_f32_16x16x32_bf16 v[16:19], v[226:229], v[164:167], v[16:19]
	v_mfma_f32_16x16x32_bf16 v[8:11], v[202:205], v[194:197], v[8:11]
	v_mfma_f32_16x16x32_bf16 v[0:3], v[226:229], v[194:197], v[0:3]

	s_add_i32 s53, s53, 2
	s_add_u32 s6, s6, 0x100
	s_addc_u32 s7, s7, 0
	s_add_u32 s51, s51, 0x100
	s_addc_u32 s52, s52, 0
	s_cmp_gt_u32 s53, 29
	s_barrier
	s_cbranch_scc0 .LBB0_118
	v_mov_b32_e32 v142, v210
	v_mov_b32_e32 v143, v169
	s_lshl_b32 s33, s4, 8
	s_add_i32 s33, s33, s34
	v_lshl_add_u32 v133, v142, 4, v143
	v_ashrrev_i32_e32 v198, 2, v133
	v_and_b32_e32 v192, 3, v143
	v_and_b32_e32 v128, -4, v133
	s_cmp_gt_i32 s4, 30
	v_lshl_add_u32 v226, v192, 6, v128
	v_add_u32_e32 v190, s33, v198
	s_cselect_b64 s[52:53], -1, 0
	s_cmp_gt_i32 s50, 8
	s_mov_b64 s[4:5], -1
	s_cbranch_scc0 .LBB0_419
	s_cmp_lg_u32 s50, 9
	s_cbranch_scc0 .LBB0_225
	s_cmp_gt_u32 s50, 25
	s_cbranch_scc0 .LBB0_127
	v_mul_f32_e32 v130, 0xbfb8aa3b, v120
	v_mul_f32_e32 v131, 0xbfb8aa3b, v121
	v_mul_f32_e32 v132, 0xbfb8aa3b, v122
	v_mul_f32_e32 v134, 0xbfb8aa3b, v123
	v_mul_f32_e32 v135, 0xbfb8aa3b, v112
	v_mul_f32_e32 v136, 0xbfb8aa3b, v113
	v_mul_f32_e32 v137, 0xbfb8aa3b, v114
	v_mul_f32_e32 v138, 0xbfb8aa3b, v115
	v_mul_f32_e32 v139, 0xbfb8aa3b, v104
	v_mul_f32_e32 v140, 0xbfb8aa3b, v105
	v_mul_f32_e32 v141, 0xbfb8aa3b, v106
	v_mul_f32_e32 v144, 0xbfb8aa3b, v107
	v_mul_f32_e32 v145, 0xbfb8aa3b, v96
	v_mul_f32_e32 v146, 0xbfb8aa3b, v97
	v_mul_f32_e32 v147, 0xbfb8aa3b, v98
	v_mul_f32_e32 v148, 0xbfb8aa3b, v99
	v_mul_f32_e32 v149, 0xbfb8aa3b, v88
	v_mul_f32_e32 v150, 0xbfb8aa3b, v89
	v_mul_f32_e32 v151, 0xbfb8aa3b, v90
	v_mul_f32_e32 v152, 0xbfb8aa3b, v91
	v_mul_f32_e32 v153, 0xbfb8aa3b, v80
	v_mul_f32_e32 v154, 0xbfb8aa3b, v81
	v_mul_f32_e32 v155, 0xbfb8aa3b, v82
	v_mul_f32_e32 v180, 0xbfb8aa3b, v83
	v_mul_f32_e32 v206, 0xbfb8aa3b, v72
	v_mul_f32_e32 v207, 0xbfb8aa3b, v73
	v_mul_f32_e32 v208, 0xbfb8aa3b, v74
	v_mul_f32_e32 v209, 0xbfb8aa3b, v75
	v_mul_f32_e32 v227, 0xbfb8aa3b, v64
	v_mul_f32_e32 v228, 0xbfb8aa3b, v65
	v_mul_f32_e32 v229, 0xbfb8aa3b, v66
	v_mul_f32_e32 v230, 0xbfb8aa3b, v67
	v_exp_f32_e32 v205, v130
	v_exp_f32_e32 v204, v131
	v_exp_f32_e32 v203, v132
	v_exp_f32_e32 v202, v134
	v_exp_f32_e32 v200, v135
	v_exp_f32_e32 v199, v136
	v_exp_f32_e32 v197, v137
	v_exp_f32_e32 v196, v138
	v_exp_f32_e32 v195, v139
	v_exp_f32_e32 v194, v140
	v_exp_f32_e32 v193, v141
	v_exp_f32_e32 v167, v144
	v_exp_f32_e32 v166, v145
	v_exp_f32_e32 v165, v146
	v_exp_f32_e32 v164, v147
	v_exp_f32_e32 v163, v148
	v_exp_f32_e32 v162, v149
	v_exp_f32_e32 v161, v150
	v_exp_f32_e32 v160, v151
	v_exp_f32_e32 v159, v152
	v_exp_f32_e32 v158, v153
	v_exp_f32_e32 v157, v154
	v_exp_f32_e32 v156, v155
	v_exp_f32_e32 v155, v180
	v_exp_f32_e32 v154, v206
	v_exp_f32_e32 v153, v207
	v_exp_f32_e32 v152, v208
	v_exp_f32_e32 v151, v209
	v_exp_f32_e32 v150, v227
	v_exp_f32_e32 v149, v228
	v_exp_f32_e32 v148, v229
	v_exp_f32_e32 v147, v230
	v_ashrrev_i32_e32 v191, 31, v190
	s_cmp_lt_u32 s50, 42
	v_lshlrev_b32_e32 v201, 2, v192
	v_lshlrev_b64 v[128:129], 12, v[190:191]
	v_mul_f32_e32 v146, 0xbfb8aa3b, v56
	v_mul_f32_e32 v145, 0xbfb8aa3b, v57
	v_mul_f32_e32 v144, 0xbfb8aa3b, v58
	v_mul_f32_e32 v141, 0xbfb8aa3b, v59
	v_mul_f32_e32 v140, 0xbfb8aa3b, v48
	v_mul_f32_e32 v139, 0xbfb8aa3b, v49
	v_mul_f32_e32 v138, 0xbfb8aa3b, v50
	v_mul_f32_e32 v137, 0xbfb8aa3b, v51
	v_mul_f32_e32 v136, 0xbfb8aa3b, v40
	v_mul_f32_e32 v135, 0xbfb8aa3b, v41
	v_mul_f32_e32 v134, 0xbfb8aa3b, v42
	v_mul_f32_e32 v132, 0xbfb8aa3b, v43
	s_cbranch_scc1 .LBB0_124
	v_mul_f32_e32 v130, 0xbfb8aa3b, v124
	v_mul_f32_e32 v131, 0xbfb8aa3b, v125
	v_mul_f32_e32 v206, 0xbfb8aa3b, v126
	v_mul_f32_e32 v207, 0xbfb8aa3b, v127
	v_exp_f32_e32 v130, v130
	v_exp_f32_e32 v131, v131
	v_exp_f32_e32 v206, v206
	v_exp_f32_e32 v207, v207
	v_add_f32_e32 v130, 1.0, v130
	v_add_f32_e32 v131, 1.0, v131
	v_add_f32_e32 v206, 1.0, v206
	v_add_f32_e32 v207, 1.0, v207
	v_rcp_f32_e32 v130, v130
	v_rcp_f32_e32 v131, v131
	v_rcp_f32_e32 v206, v206
	v_rcp_f32_e32 v207, v207
	s_lshl_b32 s4, s50, 8
	v_cvt_pk_bf16_f32 v130, v130, v131
	s_add_i32 s4, s28, s4
	v_cvt_pk_bf16_f32 v131, v206, v207
	ds_bpermute_b32 v206, v226, v130
	ds_bpermute_b32 v207, v226, v131
	v_or_b32_e32 v180, s4, v201
	v_lshl_add_u64 v[130:131], s[40:41], 0, v[128:129]
	v_lshlrev_b64 v[208:209], 1, v[180:181]
	v_lshl_add_u64 v[130:131], v[130:131], 0, v[208:209]
	s_waitcnt lgkmcnt(0)
	global_store_dwordx2 v[130:131], v[206:207], off
	v_mul_f32_e32 v180, 0xbfb8aa3b, v116
	v_mul_f32_e32 v206, 0xbfb8aa3b, v117
	v_mul_f32_e32 v207, 0xbfb8aa3b, v118
	v_mul_f32_e32 v208, 0xbfb8aa3b, v119
	v_exp_f32_e32 v180, v180
	v_exp_f32_e32 v206, v206
	v_exp_f32_e32 v207, v207
	v_exp_f32_e32 v208, v208
	v_add_f32_e32 v180, 1.0, v180
	v_add_f32_e32 v206, 1.0, v206
	v_add_f32_e32 v207, 1.0, v207
	v_add_f32_e32 v208, 1.0, v208
	v_rcp_f32_e32 v180, v180
	v_rcp_f32_e32 v206, v206
	v_rcp_f32_e32 v207, v207
	v_rcp_f32_e32 v208, v208
	s_mov_b64 s[4:5], 0x10000
	v_cvt_pk_bf16_f32 v180, v180, v206
	ds_bpermute_b32 v206, v226, v180
	v_cvt_pk_bf16_f32 v207, v207, v208
	ds_bpermute_b32 v207, v226, v207
	v_add_f32_e32 v180, 1.0, v205
	v_add_f32_e32 v208, 1.0, v202
	v_rcp_f32_e32 v180, v180
	v_rcp_f32_e32 v208, v208
	s_waitcnt lgkmcnt(0)
	global_store_dwordx2 v[130:131], v[206:207], off offset:32
	v_add_f32_e32 v206, 1.0, v204
	v_add_f32_e32 v207, 1.0, v203
	v_rcp_f32_e32 v206, v206
	v_rcp_f32_e32 v207, v207
	v_mul_f32_e32 v227, 0xbfb8aa3b, v103
	v_exp_f32_e32 v227, v227
	v_cvt_pk_bf16_f32 v180, v180, v206
	v_cvt_pk_bf16_f32 v207, v207, v208
	ds_bpermute_b32 v206, v226, v180
	ds_bpermute_b32 v207, v226, v207
	v_add_f32_e32 v180, 1.0, v200
	v_add_f32_e32 v208, 1.0, v196
	v_rcp_f32_e32 v180, v180
	v_rcp_f32_e32 v208, v208
	s_waitcnt lgkmcnt(0)
	global_store_dwordx2 v[130:131], v[206:207], off offset:256
	v_add_f32_e32 v206, 1.0, v199
	v_add_f32_e32 v207, 1.0, v197
	v_rcp_f32_e32 v206, v206
	v_rcp_f32_e32 v207, v207
	v_add_f32_e32 v227, 1.0, v227
	v_rcp_f32_e32 v227, v227
	v_cvt_pk_bf16_f32 v180, v180, v206
	v_cvt_pk_bf16_f32 v207, v207, v208
	ds_bpermute_b32 v206, v226, v180
	ds_bpermute_b32 v207, v226, v207
	v_mul_f32_e32 v180, 0xbfb8aa3b, v108
	v_mul_f32_e32 v208, 0xbfb8aa3b, v111
	v_exp_f32_e32 v180, v180
	v_exp_f32_e32 v208, v208
	s_waitcnt lgkmcnt(0)
	global_store_dwordx2 v[130:131], v[206:207], off offset:288
	v_mul_f32_e32 v206, 0xbfb8aa3b, v109
	v_mul_f32_e32 v207, 0xbfb8aa3b, v110
	v_exp_f32_e32 v206, v206
	v_exp_f32_e32 v207, v207
	v_add_f32_e32 v180, 1.0, v180
	v_add_f32_e32 v208, 1.0, v208
	v_add_f32_e32 v206, 1.0, v206
	v_add_f32_e32 v207, 1.0, v207
	v_rcp_f32_e32 v180, v180
	v_rcp_f32_e32 v206, v206
	v_rcp_f32_e32 v207, v207
	v_rcp_f32_e32 v208, v208
	v_cvt_pk_bf16_f32 v180, v180, v206
	ds_bpermute_b32 v206, v226, v180
	v_cvt_pk_bf16_f32 v207, v207, v208
	ds_bpermute_b32 v207, v226, v207
	v_lshl_add_u64 v[208:209], v[130:131], 0, s[4:5]
	s_mov_b32 s4, 0x10000
	v_add_co_u32_e32 v228, vcc, s4, v130
	v_mul_f32_e32 v180, 0xbfb8aa3b, v100
	s_nop 0
	v_addc_co_u32_e32 v229, vcc, 0, v131, vcc
	s_waitcnt lgkmcnt(0)
	global_store_dwordx2 v[228:229], v[206:207], off
	v_mul_f32_e32 v206, 0xbfb8aa3b, v101
	v_mul_f32_e32 v207, 0xbfb8aa3b, v102
	v_exp_f32_e32 v180, v180
	v_exp_f32_e32 v206, v206
	v_exp_f32_e32 v207, v207
	s_mov_b64 s[4:5], 0x20000
	v_add_f32_e32 v180, 1.0, v180
	v_add_f32_e32 v206, 1.0, v206
	v_add_f32_e32 v207, 1.0, v207
	v_rcp_f32_e32 v180, v180
	v_rcp_f32_e32 v206, v206
	v_rcp_f32_e32 v207, v207
	v_cvt_pk_bf16_f32 v180, v180, v206
	v_cvt_pk_bf16_f32 v207, v207, v227
	ds_bpermute_b32 v206, v226, v180
	ds_bpermute_b32 v207, v226, v207
	v_add_f32_e32 v180, 1.0, v195
	v_add_f32_e32 v227, 1.0, v167
	v_rcp_f32_e32 v180, v180
	v_rcp_f32_e32 v227, v227
	s_waitcnt lgkmcnt(0)
	global_store_dwordx2 v[208:209], v[206:207], off offset:32
	v_add_f32_e32 v206, 1.0, v194
	v_add_f32_e32 v207, 1.0, v193
	v_rcp_f32_e32 v206, v206
	v_rcp_f32_e32 v207, v207
	v_cvt_pk_bf16_f32 v180, v180, v206
	v_cvt_pk_bf16_f32 v207, v207, v227
	ds_bpermute_b32 v206, v226, v180
	ds_bpermute_b32 v207, v226, v207
	v_add_f32_e32 v180, 1.0, v166
	v_add_f32_e32 v227, 1.0, v163
	v_rcp_f32_e32 v180, v180
	v_rcp_f32_e32 v227, v227
	s_waitcnt lgkmcnt(0)
	global_store_dwordx2 v[208:209], v[206:207], off offset:256
	v_add_f32_e32 v206, 1.0, v165
	v_add_f32_e32 v207, 1.0, v164
	v_rcp_f32_e32 v206, v206
	v_rcp_f32_e32 v207, v207
	v_cvt_pk_bf16_f32 v180, v180, v206
	v_cvt_pk_bf16_f32 v207, v207, v227
	ds_bpermute_b32 v206, v226, v180
	ds_bpermute_b32 v207, v226, v207
	v_mul_f32_e32 v180, 0xbfb8aa3b, v92
	v_exp_f32_e32 v180, v180
	v_mul_f32_e32 v227, 0xbfb8aa3b, v87
	v_exp_f32_e32 v227, v227
	s_waitcnt lgkmcnt(0)
	global_store_dwordx2 v[208:209], v[206:207], off offset:288
	v_mul_f32_e32 v206, 0xbfb8aa3b, v93
	v_mul_f32_e32 v207, 0xbfb8aa3b, v94
	v_mul_f32_e32 v208, 0xbfb8aa3b, v95
	v_exp_f32_e32 v206, v206
	v_exp_f32_e32 v207, v207
	v_exp_f32_e32 v208, v208
	v_add_f32_e32 v180, 1.0, v180
	v_add_f32_e32 v206, 1.0, v206
	v_add_f32_e32 v207, 1.0, v207
	v_add_f32_e32 v208, 1.0, v208
	v_rcp_f32_e32 v180, v180
	v_rcp_f32_e32 v206, v206
	v_rcp_f32_e32 v207, v207
	v_rcp_f32_e32 v208, v208
	v_add_f32_e32 v227, 1.0, v227
	v_cvt_pk_bf16_f32 v180, v180, v206
	ds_bpermute_b32 v206, v226, v180
	v_cvt_pk_bf16_f32 v207, v207, v208
	ds_bpermute_b32 v207, v226, v207
	v_lshl_add_u64 v[208:209], v[130:131], 0, s[4:5]
	s_mov_b32 s4, 0x20000
	v_add_co_u32_e32 v228, vcc, s4, v130
	v_mul_f32_e32 v180, 0xbfb8aa3b, v84
	s_nop 0
	v_addc_co_u32_e32 v229, vcc, 0, v131, vcc
	s_waitcnt lgkmcnt(0)
	global_store_dwordx2 v[228:229], v[206:207], off
	v_mul_f32_e32 v206, 0xbfb8aa3b, v85
	v_mul_f32_e32 v207, 0xbfb8aa3b, v86
	v_exp_f32_e32 v180, v180
	v_exp_f32_e32 v206, v206
	v_exp_f32_e32 v207, v207
	v_rcp_f32_e32 v227, v227
	v_add_f32_e32 v180, 1.0, v180
	v_add_f32_e32 v206, 1.0, v206
	v_add_f32_e32 v207, 1.0, v207
	v_rcp_f32_e32 v180, v180
	v_rcp_f32_e32 v206, v206
	v_rcp_f32_e32 v207, v207
	s_mov_b64 s[4:5], 0x30000
	v_cvt_pk_bf16_f32 v180, v180, v206
	v_cvt_pk_bf16_f32 v207, v207, v227
	ds_bpermute_b32 v206, v226, v180
	ds_bpermute_b32 v207, v226, v207
	v_add_f32_e32 v180, 1.0, v162
	v_add_f32_e32 v227, 1.0, v159
	v_rcp_f32_e32 v180, v180
	v_rcp_f32_e32 v227, v227
	s_waitcnt lgkmcnt(0)
	global_store_dwordx2 v[208:209], v[206:207], off offset:32
	v_add_f32_e32 v206, 1.0, v161
	v_add_f32_e32 v207, 1.0, v160
	v_rcp_f32_e32 v206, v206
	v_rcp_f32_e32 v207, v207
	v_cvt_pk_bf16_f32 v180, v180, v206
	v_cvt_pk_bf16_f32 v207, v207, v227
	ds_bpermute_b32 v206, v226, v180
	ds_bpermute_b32 v207, v226, v207
	v_add_f32_e32 v180, 1.0, v158
	v_add_f32_e32 v227, 1.0, v155
	v_rcp_f32_e32 v180, v180
	v_rcp_f32_e32 v227, v227
	s_waitcnt lgkmcnt(0)
	global_store_dwordx2 v[208:209], v[206:207], off offset:256
	v_add_f32_e32 v206, 1.0, v157
	v_add_f32_e32 v207, 1.0, v156
	v_rcp_f32_e32 v206, v206
	v_rcp_f32_e32 v207, v207
	v_cvt_pk_bf16_f32 v180, v180, v206
	v_cvt_pk_bf16_f32 v207, v207, v227
	ds_bpermute_b32 v206, v226, v180
	ds_bpermute_b32 v207, v226, v207
	v_mul_f32_e32 v180, 0xbfb8aa3b, v76
	v_exp_f32_e32 v180, v180
	v_mul_f32_e32 v227, 0xbfb8aa3b, v71
	v_exp_f32_e32 v227, v227
	s_waitcnt lgkmcnt(0)
	global_store_dwordx2 v[208:209], v[206:207], off offset:288
	v_mul_f32_e32 v206, 0xbfb8aa3b, v77
	v_mul_f32_e32 v207, 0xbfb8aa3b, v78
	v_mul_f32_e32 v208, 0xbfb8aa3b, v79
	v_exp_f32_e32 v206, v206
	v_exp_f32_e32 v207, v207
	v_exp_f32_e32 v208, v208
	v_add_f32_e32 v180, 1.0, v180
	v_add_f32_e32 v206, 1.0, v206
	v_add_f32_e32 v207, 1.0, v207
	v_add_f32_e32 v208, 1.0, v208
	v_rcp_f32_e32 v180, v180
	v_rcp_f32_e32 v206, v206
	v_rcp_f32_e32 v207, v207
	v_rcp_f32_e32 v208, v208
	v_add_f32_e32 v227, 1.0, v227
	v_cvt_pk_bf16_f32 v180, v180, v206
	ds_bpermute_b32 v206, v226, v180
	v_cvt_pk_bf16_f32 v207, v207, v208
	ds_bpermute_b32 v207, v226, v207
	v_lshl_add_u64 v[208:209], v[130:131], 0, s[4:5]
	s_mov_b32 s4, 0x30000
	v_add_co_u32_e32 v228, vcc, s4, v130
	v_mul_f32_e32 v180, 0xbfb8aa3b, v68
	s_nop 0
	v_addc_co_u32_e32 v229, vcc, 0, v131, vcc
	s_waitcnt lgkmcnt(0)
	global_store_dwordx2 v[228:229], v[206:207], off
	v_mul_f32_e32 v206, 0xbfb8aa3b, v69
	v_mul_f32_e32 v207, 0xbfb8aa3b, v70
	v_exp_f32_e32 v180, v180
	v_exp_f32_e32 v206, v206
	v_exp_f32_e32 v207, v207
	v_rcp_f32_e32 v227, v227
	v_add_f32_e32 v180, 1.0, v180
	v_add_f32_e32 v206, 1.0, v206
	v_add_f32_e32 v207, 1.0, v207
	v_rcp_f32_e32 v180, v180
	v_rcp_f32_e32 v206, v206
	v_rcp_f32_e32 v207, v207
	s_mov_b64 s[4:5], 0x80000
	v_cvt_pk_bf16_f32 v180, v180, v206
	v_cvt_pk_bf16_f32 v207, v207, v227
	ds_bpermute_b32 v206, v226, v180
	ds_bpermute_b32 v207, v226, v207
	v_add_f32_e32 v180, 1.0, v154
	v_add_f32_e32 v227, 1.0, v151
	v_rcp_f32_e32 v180, v180
	v_rcp_f32_e32 v227, v227
	s_waitcnt lgkmcnt(0)
	global_store_dwordx2 v[208:209], v[206:207], off offset:32
	v_add_f32_e32 v206, 1.0, v153
	v_add_f32_e32 v207, 1.0, v152
	v_rcp_f32_e32 v206, v206
	v_rcp_f32_e32 v207, v207
	v_cvt_pk_bf16_f32 v180, v180, v206
	v_cvt_pk_bf16_f32 v207, v207, v227
	ds_bpermute_b32 v206, v226, v180
	ds_bpermute_b32 v207, v226, v207
	v_add_f32_e32 v180, 1.0, v150
	v_add_f32_e32 v227, 1.0, v147
	v_rcp_f32_e32 v180, v180
	v_rcp_f32_e32 v227, v227
	s_waitcnt lgkmcnt(0)
	global_store_dwordx2 v[208:209], v[206:207], off offset:256
	v_add_f32_e32 v206, 1.0, v149
	v_add_f32_e32 v207, 1.0, v148
	v_rcp_f32_e32 v206, v206
	v_rcp_f32_e32 v207, v207
	v_cvt_pk_bf16_f32 v180, v180, v206
	v_cvt_pk_bf16_f32 v207, v207, v227
	ds_bpermute_b32 v206, v226, v180
	ds_bpermute_b32 v207, v226, v207
	v_mul_f32_e32 v180, 0xbfb8aa3b, v60
	v_exp_f32_e32 v180, v180
	v_mul_f32_e32 v227, 0xbfb8aa3b, v55
	v_exp_f32_e32 v227, v227
	s_waitcnt lgkmcnt(0)
	global_store_dwordx2 v[208:209], v[206:207], off offset:288
	v_mul_f32_e32 v206, 0xbfb8aa3b, v61
	v_mul_f32_e32 v207, 0xbfb8aa3b, v62
	v_mul_f32_e32 v208, 0xbfb8aa3b, v63
	v_exp_f32_e32 v206, v206
	v_exp_f32_e32 v207, v207
	v_exp_f32_e32 v208, v208
	v_add_f32_e32 v180, 1.0, v180
	v_add_f32_e32 v206, 1.0, v206
	v_add_f32_e32 v207, 1.0, v207
	v_add_f32_e32 v208, 1.0, v208
	v_rcp_f32_e32 v180, v180
	v_rcp_f32_e32 v206, v206
	v_rcp_f32_e32 v207, v207
	v_rcp_f32_e32 v208, v208
	v_add_f32_e32 v227, 1.0, v227
	v_cvt_pk_bf16_f32 v180, v180, v206
	ds_bpermute_b32 v206, v226, v180
	v_cvt_pk_bf16_f32 v207, v207, v208
	ds_bpermute_b32 v207, v226, v207
	v_lshl_add_u64 v[208:209], v[130:131], 0, s[4:5]
	s_mov_b32 s4, 0x80000
	v_add_co_u32_e32 v228, vcc, s4, v130
	v_mul_f32_e32 v180, 0xbfb8aa3b, v52
	s_nop 0
	v_addc_co_u32_e32 v229, vcc, 0, v131, vcc
	s_waitcnt lgkmcnt(0)
	global_store_dwordx2 v[228:229], v[206:207], off
	v_mul_f32_e32 v206, 0xbfb8aa3b, v53
	v_mul_f32_e32 v207, 0xbfb8aa3b, v54
	v_exp_f32_e32 v180, v180
	v_exp_f32_e32 v206, v206
	v_exp_f32_e32 v207, v207
	v_rcp_f32_e32 v227, v227
	v_add_f32_e32 v180, 1.0, v180
	v_add_f32_e32 v206, 1.0, v206
	v_add_f32_e32 v207, 1.0, v207
	v_rcp_f32_e32 v180, v180
	v_rcp_f32_e32 v206, v206
	v_rcp_f32_e32 v207, v207
	s_mov_b64 s[4:5], 0x90000
	v_cvt_pk_bf16_f32 v180, v180, v206
	v_cvt_pk_bf16_f32 v207, v207, v227
	ds_bpermute_b32 v206, v226, v180
	ds_bpermute_b32 v207, v226, v207
	v_exp_f32_e32 v180, v146
	v_exp_f32_e32 v227, v141
	s_waitcnt lgkmcnt(0)
	global_store_dwordx2 v[208:209], v[206:207], off offset:32
	v_exp_f32_e32 v206, v145
	v_exp_f32_e32 v207, v144
	v_add_f32_e32 v180, 1.0, v180
	v_add_f32_e32 v227, 1.0, v227
	v_add_f32_e32 v206, 1.0, v206
	v_add_f32_e32 v207, 1.0, v207
	v_rcp_f32_e32 v180, v180
	v_rcp_f32_e32 v206, v206
	v_rcp_f32_e32 v207, v207
	v_rcp_f32_e32 v227, v227
	v_cvt_pk_bf16_f32 v180, v180, v206
	ds_bpermute_b32 v206, v226, v180
	v_cvt_pk_bf16_f32 v207, v207, v227
	ds_bpermute_b32 v207, v226, v207
	v_exp_f32_e32 v180, v140
	v_exp_f32_e32 v227, v137
	s_waitcnt lgkmcnt(0)
	global_store_dwordx2 v[208:209], v[206:207], off offset:256
	v_exp_f32_e32 v206, v139
	v_exp_f32_e32 v207, v138
	v_add_f32_e32 v180, 1.0, v180
	v_add_f32_e32 v227, 1.0, v227
	v_add_f32_e32 v206, 1.0, v206
	v_add_f32_e32 v207, 1.0, v207
	v_rcp_f32_e32 v180, v180
	v_rcp_f32_e32 v206, v206
	v_rcp_f32_e32 v207, v207
	v_rcp_f32_e32 v227, v227
	v_cvt_pk_bf16_f32 v180, v180, v206
	ds_bpermute_b32 v206, v226, v180
	v_cvt_pk_bf16_f32 v207, v207, v227
	ds_bpermute_b32 v207, v226, v207
	v_mul_f32_e32 v180, 0xbfb8aa3b, v44
	v_exp_f32_e32 v180, v180
	v_mul_f32_e32 v227, 0xbfb8aa3b, v39
	v_exp_f32_e32 v227, v227
	s_waitcnt lgkmcnt(0)
	global_store_dwordx2 v[208:209], v[206:207], off offset:288
	v_mul_f32_e32 v206, 0xbfb8aa3b, v45
	v_mul_f32_e32 v207, 0xbfb8aa3b, v46
	v_mul_f32_e32 v208, 0xbfb8aa3b, v47
	v_exp_f32_e32 v206, v206
	v_exp_f32_e32 v207, v207
	v_exp_f32_e32 v208, v208
	v_add_f32_e32 v180, 1.0, v180
	v_add_f32_e32 v206, 1.0, v206
	v_add_f32_e32 v207, 1.0, v207
	v_add_f32_e32 v208, 1.0, v208
	v_rcp_f32_e32 v180, v180
	v_rcp_f32_e32 v206, v206
	v_rcp_f32_e32 v207, v207
	v_rcp_f32_e32 v208, v208
	v_add_f32_e32 v227, 1.0, v227
	v_cvt_pk_bf16_f32 v180, v180, v206
	ds_bpermute_b32 v206, v226, v180
	v_cvt_pk_bf16_f32 v207, v207, v208
	ds_bpermute_b32 v207, v226, v207
	v_lshl_add_u64 v[208:209], v[130:131], 0, s[4:5]
	s_mov_b32 s4, 0x90000
	v_add_co_u32_e32 v228, vcc, s4, v130
	v_mul_f32_e32 v180, 0xbfb8aa3b, v36
	s_nop 0
	v_addc_co_u32_e32 v229, vcc, 0, v131, vcc
	s_waitcnt lgkmcnt(0)
	global_store_dwordx2 v[228:229], v[206:207], off
	v_mul_f32_e32 v206, 0xbfb8aa3b, v37
	v_mul_f32_e32 v207, 0xbfb8aa3b, v38
	v_exp_f32_e32 v180, v180
	v_exp_f32_e32 v206, v206
	v_exp_f32_e32 v207, v207
	v_rcp_f32_e32 v227, v227
	v_add_f32_e32 v180, 1.0, v180
	v_add_f32_e32 v206, 1.0, v206
	v_add_f32_e32 v207, 1.0, v207
	v_rcp_f32_e32 v180, v180
	v_rcp_f32_e32 v206, v206
	v_rcp_f32_e32 v207, v207
	s_mov_b64 s[4:5], 0xa0000
	v_cvt_pk_bf16_f32 v180, v180, v206
	v_cvt_pk_bf16_f32 v207, v207, v227
	ds_bpermute_b32 v206, v226, v180
	ds_bpermute_b32 v207, v226, v207
	v_exp_f32_e32 v180, v136
	v_exp_f32_e32 v227, v132
	s_waitcnt lgkmcnt(0)
	global_store_dwordx2 v[208:209], v[206:207], off offset:32
	v_exp_f32_e32 v206, v135
	v_exp_f32_e32 v207, v134
	v_add_f32_e32 v180, 1.0, v180
	v_add_f32_e32 v227, 1.0, v227
	v_add_f32_e32 v206, 1.0, v206
	v_add_f32_e32 v207, 1.0, v207
	v_rcp_f32_e32 v180, v180
	v_rcp_f32_e32 v206, v206
	v_rcp_f32_e32 v207, v207
	v_rcp_f32_e32 v227, v227
	v_cvt_pk_bf16_f32 v180, v180, v206
	ds_bpermute_b32 v206, v226, v180
	v_cvt_pk_bf16_f32 v207, v207, v227
	ds_bpermute_b32 v207, v226, v207
	v_mul_f32_e32 v180, 0xbfb8aa3b, v32
	v_mul_f32_e32 v227, 0xbfb8aa3b, v35
	v_exp_f32_e32 v180, v180
	v_exp_f32_e32 v227, v227
	s_waitcnt lgkmcnt(0)
	global_store_dwordx2 v[208:209], v[206:207], off offset:256
	v_mul_f32_e32 v206, 0xbfb8aa3b, v33
	v_mul_f32_e32 v207, 0xbfb8aa3b, v34
	v_exp_f32_e32 v206, v206
	v_exp_f32_e32 v207, v207
	v_add_f32_e32 v180, 1.0, v180
	v_add_f32_e32 v227, 1.0, v227
	v_add_f32_e32 v206, 1.0, v206
	v_add_f32_e32 v207, 1.0, v207
	v_rcp_f32_e32 v180, v180
	v_rcp_f32_e32 v206, v206
	v_rcp_f32_e32 v207, v207
	v_rcp_f32_e32 v227, v227
	v_cvt_pk_bf16_f32 v180, v180, v206
	ds_bpermute_b32 v206, v226, v180
	v_cvt_pk_bf16_f32 v207, v207, v227
	ds_bpermute_b32 v207, v226, v207
	v_mul_f32_e32 v180, 0xbfb8aa3b, v28
	v_exp_f32_e32 v180, v180
	v_mul_f32_e32 v227, 0xbfb8aa3b, v23
	v_exp_f32_e32 v227, v227
	s_waitcnt lgkmcnt(0)
	global_store_dwordx2 v[208:209], v[206:207], off offset:288
	v_mul_f32_e32 v206, 0xbfb8aa3b, v29
	v_mul_f32_e32 v207, 0xbfb8aa3b, v30
	v_mul_f32_e32 v208, 0xbfb8aa3b, v31
	v_exp_f32_e32 v206, v206
	v_exp_f32_e32 v207, v207
	v_exp_f32_e32 v208, v208
	v_add_f32_e32 v180, 1.0, v180
	v_add_f32_e32 v206, 1.0, v206
	v_add_f32_e32 v207, 1.0, v207
	v_add_f32_e32 v208, 1.0, v208
	v_rcp_f32_e32 v180, v180
	v_rcp_f32_e32 v206, v206
	v_rcp_f32_e32 v207, v207
	v_rcp_f32_e32 v208, v208
	v_add_f32_e32 v227, 1.0, v227
	v_cvt_pk_bf16_f32 v180, v180, v206
	ds_bpermute_b32 v206, v226, v180
	v_cvt_pk_bf16_f32 v207, v207, v208
	ds_bpermute_b32 v207, v226, v207
	v_lshl_add_u64 v[208:209], v[130:131], 0, s[4:5]
	s_mov_b32 s4, 0xa0000
	v_add_co_u32_e32 v228, vcc, s4, v130
	v_mul_f32_e32 v180, 0xbfb8aa3b, v20
	s_nop 0
	v_addc_co_u32_e32 v229, vcc, 0, v131, vcc
	s_waitcnt lgkmcnt(0)
	global_store_dwordx2 v[228:229], v[206:207], off
	v_mul_f32_e32 v206, 0xbfb8aa3b, v21
	v_mul_f32_e32 v207, 0xbfb8aa3b, v22
	v_exp_f32_e32 v180, v180
	v_exp_f32_e32 v206, v206
	v_exp_f32_e32 v207, v207
	v_rcp_f32_e32 v227, v227
	v_add_f32_e32 v180, 1.0, v180
	v_add_f32_e32 v206, 1.0, v206
	v_add_f32_e32 v207, 1.0, v207
	v_rcp_f32_e32 v180, v180
	v_rcp_f32_e32 v206, v206
	v_rcp_f32_e32 v207, v207
	s_mov_b64 s[4:5], 0xb0000
	v_cvt_pk_bf16_f32 v180, v180, v206
	v_cvt_pk_bf16_f32 v207, v207, v227
	ds_bpermute_b32 v206, v226, v180
	ds_bpermute_b32 v207, v226, v207
	v_mul_f32_e32 v180, 0xbfb8aa3b, v24
	v_mul_f32_e32 v227, 0xbfb8aa3b, v27
	v_exp_f32_e32 v180, v180
	v_exp_f32_e32 v227, v227
	s_waitcnt lgkmcnt(0)
	global_store_dwordx2 v[208:209], v[206:207], off offset:32
	v_mul_f32_e32 v206, 0xbfb8aa3b, v25
	v_mul_f32_e32 v207, 0xbfb8aa3b, v26
	v_exp_f32_e32 v206, v206
	v_exp_f32_e32 v207, v207
	v_add_f32_e32 v180, 1.0, v180
	v_add_f32_e32 v227, 1.0, v227
	v_add_f32_e32 v206, 1.0, v206
	v_add_f32_e32 v207, 1.0, v207
	v_rcp_f32_e32 v180, v180
	v_rcp_f32_e32 v206, v206
	v_rcp_f32_e32 v207, v207
	v_rcp_f32_e32 v227, v227
	v_cvt_pk_bf16_f32 v180, v180, v206
	ds_bpermute_b32 v206, v226, v180
	v_cvt_pk_bf16_f32 v207, v207, v227
	ds_bpermute_b32 v207, v226, v207
	v_mul_f32_e32 v180, 0xbfb8aa3b, v16
	v_mul_f32_e32 v227, 0xbfb8aa3b, v19
	v_exp_f32_e32 v180, v180
	v_exp_f32_e32 v227, v227
	s_waitcnt lgkmcnt(0)
	global_store_dwordx2 v[208:209], v[206:207], off offset:256
	v_mul_f32_e32 v206, 0xbfb8aa3b, v17
	v_mul_f32_e32 v207, 0xbfb8aa3b, v18
	v_exp_f32_e32 v206, v206
	v_exp_f32_e32 v207, v207
	v_add_f32_e32 v180, 1.0, v180
	v_add_f32_e32 v227, 1.0, v227
	v_add_f32_e32 v206, 1.0, v206
	v_add_f32_e32 v207, 1.0, v207
	v_rcp_f32_e32 v180, v180
	v_rcp_f32_e32 v206, v206
	v_rcp_f32_e32 v207, v207
	v_rcp_f32_e32 v227, v227
	v_cvt_pk_bf16_f32 v180, v180, v206
	ds_bpermute_b32 v206, v226, v180
	v_cvt_pk_bf16_f32 v207, v207, v227
	ds_bpermute_b32 v207, v226, v207
	v_mul_f32_e32 v180, 0xbfb8aa3b, v12
	v_exp_f32_e32 v180, v180
	s_waitcnt lgkmcnt(0)
	global_store_dwordx2 v[208:209], v[206:207], off offset:288
	v_mul_f32_e32 v206, 0xbfb8aa3b, v13
	v_mul_f32_e32 v207, 0xbfb8aa3b, v14
	v_mul_f32_e32 v208, 0xbfb8aa3b, v15
	v_exp_f32_e32 v206, v206
	v_exp_f32_e32 v207, v207
	v_exp_f32_e32 v208, v208
	v_add_f32_e32 v180, 1.0, v180
	v_add_f32_e32 v206, 1.0, v206
	v_add_f32_e32 v207, 1.0, v207
	v_add_f32_e32 v208, 1.0, v208
	v_rcp_f32_e32 v180, v180
	v_rcp_f32_e32 v206, v206
	v_rcp_f32_e32 v207, v207
	v_rcp_f32_e32 v208, v208
	v_cvt_pk_bf16_f32 v180, v180, v206
	ds_bpermute_b32 v206, v226, v180
	v_cvt_pk_bf16_f32 v207, v207, v208
	ds_bpermute_b32 v207, v226, v207
	v_lshl_add_u64 v[208:209], v[130:131], 0, s[4:5]
	s_mov_b32 s4, 0xb0000
	v_add_co_u32_e32 v130, vcc, s4, v130
	v_mul_f32_e32 v180, 0xbfb8aa3b, v6
	s_nop 0
	v_addc_co_u32_e32 v131, vcc, 0, v131, vcc
	s_waitcnt lgkmcnt(0)
	global_store_dwordx2 v[130:131], v[206:207], off
	v_mul_f32_e32 v130, 0xbfb8aa3b, v4
	v_mul_f32_e32 v131, 0xbfb8aa3b, v5
	v_mul_f32_e32 v206, 0xbfb8aa3b, v7
	v_exp_f32_e32 v130, v130
	v_exp_f32_e32 v131, v131
	v_exp_f32_e32 v180, v180
	v_exp_f32_e32 v206, v206
	v_add_f32_e32 v130, 1.0, v130
	v_add_f32_e32 v131, 1.0, v131
	v_add_f32_e32 v180, 1.0, v180
	v_add_f32_e32 v206, 1.0, v206
	v_rcp_f32_e32 v130, v130
	v_rcp_f32_e32 v131, v131
	v_rcp_f32_e32 v180, v180
	v_rcp_f32_e32 v206, v206
	s_mov_b64 s[4:5], 0
	v_cvt_pk_bf16_f32 v130, v130, v131
	ds_bpermute_b32 v130, v226, v130
	v_cvt_pk_bf16_f32 v131, v180, v206
	ds_bpermute_b32 v131, v226, v131
	v_mul_f32_e32 v180, 0xbfb8aa3b, v10
	v_mul_f32_e32 v206, 0xbfb8aa3b, v11
	v_exp_f32_e32 v180, v180
	v_exp_f32_e32 v206, v206
	s_waitcnt lgkmcnt(0)
	global_store_dwordx2 v[208:209], v[130:131], off offset:32
	v_mul_f32_e32 v130, 0xbfb8aa3b, v8
	v_mul_f32_e32 v131, 0xbfb8aa3b, v9
	v_exp_f32_e32 v130, v130
	v_exp_f32_e32 v131, v131
	v_add_f32_e32 v180, 1.0, v180
	v_add_f32_e32 v206, 1.0, v206
	v_add_f32_e32 v130, 1.0, v130
	v_add_f32_e32 v131, 1.0, v131
	v_rcp_f32_e32 v130, v130
	v_rcp_f32_e32 v131, v131
	v_rcp_f32_e32 v180, v180
	v_rcp_f32_e32 v206, v206
	v_cvt_pk_bf16_f32 v130, v130, v131
	ds_bpermute_b32 v130, v226, v130
	v_cvt_pk_bf16_f32 v131, v180, v206
	ds_bpermute_b32 v131, v226, v131
	v_mul_f32_e32 v180, 0xbfb8aa3b, v2
	v_mul_f32_e32 v206, 0xbfb8aa3b, v3
	v_exp_f32_e32 v180, v180
	v_exp_f32_e32 v206, v206
	s_waitcnt lgkmcnt(0)
	global_store_dwordx2 v[208:209], v[130:131], off offset:256
	v_mul_f32_e32 v130, 0xbfb8aa3b, v0
	v_mul_f32_e32 v131, 0xbfb8aa3b, v1
	v_exp_f32_e32 v130, v130
	v_exp_f32_e32 v131, v131
	v_add_f32_e32 v180, 1.0, v180
	v_add_f32_e32 v206, 1.0, v206
	v_add_f32_e32 v130, 1.0, v130
	v_add_f32_e32 v131, 1.0, v131
	v_rcp_f32_e32 v130, v130
	v_rcp_f32_e32 v131, v131
	v_rcp_f32_e32 v180, v180
	v_rcp_f32_e32 v206, v206
	v_cvt_pk_bf16_f32 v130, v130, v131
	ds_bpermute_b32 v130, v226, v130
	v_cvt_pk_bf16_f32 v131, v180, v206
	ds_bpermute_b32 v131, v226, v131
	s_waitcnt lgkmcnt(0)
	global_store_dwordx2 v[208:209], v[130:131], off offset:288

.LBB0_1024:
	s_waitcnt lgkmcnt(0)
	ds_read_b128 v[128:131], v179
	ds_read_b128 v[132:135], v179 offset:1024
	ds_read_b128 v[136:139], v179 offset:2048
	ds_read_b128 v[140:143], v179 offset:3072
	s_add_i32 s62, s36, 2
	s_add_u32 s37, s4, 0xfff80080
	s_addc_u32 s38, s5, -1
	s_cmp_eq_u32 s59, s36
	s_cselect_b32 s36, s58, s60
	s_cselect_b32 s39, s21, s38
	s_cselect_b32 s38, s25, s37
	s_cselect_b32 s37, s23, s61

	s_add_i32 m0, s31, 0xc000
	ds_read_b128 v[144:147], v190
	ds_read_b128 v[148:151], v190 offset:1024
	ds_read_b128 v[152:155], v190 offset:2048
	ds_read_b128 v[156:159], v190 offset:3072
	ds_read_b128 v[180:183], v190 offset:4096
	ds_read_b128 v[184:187], v190 offset:5120
	ds_read_b128 v[194:197], v190 offset:6144

	global_load_lds_dwordx4 v162, s[4:5]
	s_add_i32 m0, s31, 0xe000
	ds_read_b128 v[198:201], v190 offset:7168

	global_load_lds_dwordx4 v164, s[4:5]
	s_waitcnt lgkmcnt(8)
	s_barrier
	s_waitcnt lgkmcnt(0)


	v_mfma_f32_16x16x32_bf16 v[124:127], v[128:131], v[144:147], v[124:127]
	v_mfma_f32_16x16x32_bf16 v[120:123], v[136:139], v[144:147], v[120:123]
	v_mfma_f32_16x16x32_bf16 v[116:119], v[128:131], v[152:155], v[116:119]
	v_mfma_f32_16x16x32_bf16 v[104:107], v[136:139], v[152:155], v[104:107]
	v_mfma_f32_16x16x32_bf16 v[96:99], v[128:131], v[180:183], v[96:99]
	v_mfma_f32_16x16x32_bf16 v[88:91], v[136:139], v[180:183], v[88:91]
	v_mfma_f32_16x16x32_bf16 v[80:83], v[128:131], v[194:197], v[80:83]
	v_mfma_f32_16x16x32_bf16 v[72:75], v[136:139], v[194:197], v[72:75]
	v_mfma_f32_16x16x32_bf16 v[124:127], v[132:135], v[148:151], v[124:127]
	v_mfma_f32_16x16x32_bf16 v[120:123], v[140:143], v[148:151], v[120:123]
	v_mfma_f32_16x16x32_bf16 v[116:119], v[132:135], v[156:159], v[116:119]
	v_mfma_f32_16x16x32_bf16 v[104:107], v[140:143], v[156:159], v[104:107]
	v_mfma_f32_16x16x32_bf16 v[96:99], v[132:135], v[184:187], v[96:99]
	v_mfma_f32_16x16x32_bf16 v[88:91], v[140:143], v[184:187], v[88:91]
	v_mfma_f32_16x16x32_bf16 v[80:83], v[132:135], v[198:201], v[80:83]
	v_mfma_f32_16x16x32_bf16 v[72:75], v[140:143], v[198:201], v[72:75]

	s_barrier
	s_add_i32 s63, s52, s42
	s_add_u32 s66, s36, s14
	s_addc_u32 s67, s37, s15
	s_mov_b32 m0, s63
	ds_read_b128 v[202:205], v191
	ds_read_b128 v[206:209], v191 offset:1024
	ds_read_b128 v[222:225], v191 offset:2048

	global_load_lds_dwordx4 v172, s[36:37]
	s_add_i32 m0, s63, 0x2000
	ds_read_b128 v[226:229], v191 offset:3072

	global_load_lds_dwordx4 v174, s[36:37]
	s_barrier
	s_waitcnt lgkmcnt(0)


	v_mfma_f32_16x16x32_bf16 v[112:115], v[202:205], v[144:147], v[112:115]
	v_mfma_f32_16x16x32_bf16 v[108:111], v[222:225], v[144:147], v[108:111]
	v_mfma_f32_16x16x32_bf16 v[100:103], v[202:205], v[152:155], v[100:103]
	v_mfma_f32_16x16x32_bf16 v[92:95], v[222:225], v[152:155], v[92:95]
	v_mfma_f32_16x16x32_bf16 v[84:87], v[202:205], v[180:183], v[84:87]
	v_mfma_f32_16x16x32_bf16 v[76:79], v[222:225], v[180:183], v[76:79]
	v_mfma_f32_16x16x32_bf16 v[68:71], v[202:205], v[194:197], v[68:71]
	v_mfma_f32_16x16x32_bf16 v[64:67], v[222:225], v[194:197], v[64:67]
	v_mfma_f32_16x16x32_bf16 v[112:115], v[206:209], v[148:151], v[112:115]
	v_mfma_f32_16x16x32_bf16 v[108:111], v[226:229], v[148:151], v[108:111]
	v_mfma_f32_16x16x32_bf16 v[100:103], v[206:209], v[156:159], v[100:103]
	v_mfma_f32_16x16x32_bf16 v[92:95], v[226:229], v[156:159], v[92:95]
	v_mfma_f32_16x16x32_bf16 v[84:87], v[206:209], v[184:187], v[84:87]
	v_mfma_f32_16x16x32_bf16 v[76:79], v[226:229], v[184:187], v[76:79]
	v_mfma_f32_16x16x32_bf16 v[68:71], v[206:209], v[198:201], v[68:71]
	v_mfma_f32_16x16x32_bf16 v[64:67], v[226:229], v[198:201], v[64:67]

	s_mov_b32 m0, s31
	s_add_u32 s68, s38, s14
	s_addc_u32 s69, s39, s15
	s_barrier
	ds_read_b128 v[144:147], v190 offset:16384
	ds_read_b128 v[148:151], v190 offset:17408
	ds_read_b128 v[152:155], v190 offset:18432
	ds_read_b128 v[156:159], v190 offset:19456
	ds_read_b128 v[180:183], v190 offset:20480
	ds_read_b128 v[184:187], v190 offset:21504
	ds_read_b128 v[194:197], v190 offset:22528

	global_load_lds_dwordx4 v172, s[38:39]
	s_mov_b32 m0, s35
	ds_read_b128 v[198:201], v190 offset:23552

	global_load_lds_dwordx4 v174, s[38:39]
	s_barrier
	s_waitcnt lgkmcnt(0)


	v_mfma_f32_16x16x32_bf16 v[60:63], v[128:131], v[144:147], v[60:63]
	v_mfma_f32_16x16x32_bf16 v[56:59], v[136:139], v[144:147], v[56:59]
	v_mfma_f32_16x16x32_bf16 v[52:55], v[128:131], v[152:155], v[52:55]
	v_mfma_f32_16x16x32_bf16 v[40:43], v[136:139], v[152:155], v[40:43]
	v_mfma_f32_16x16x32_bf16 v[36:39], v[128:131], v[180:183], v[36:39]
	v_mfma_f32_16x16x32_bf16 v[24:27], v[136:139], v[180:183], v[24:27]
	v_mfma_f32_16x16x32_bf16 v[20:23], v[128:131], v[194:197], v[20:23]
	v_mfma_f32_16x16x32_bf16 v[8:11], v[136:139], v[194:197], v[8:11]
	v_mfma_f32_16x16x32_bf16 v[60:63], v[132:135], v[148:151], v[60:63]
	v_mfma_f32_16x16x32_bf16 v[56:59], v[140:143], v[148:151], v[56:59]
	v_mfma_f32_16x16x32_bf16 v[52:55], v[132:135], v[156:159], v[52:55]
	v_mfma_f32_16x16x32_bf16 v[40:43], v[140:143], v[156:159], v[40:43]
	v_mfma_f32_16x16x32_bf16 v[36:39], v[132:135], v[184:187], v[36:39]
	v_mfma_f32_16x16x32_bf16 v[24:27], v[140:143], v[184:187], v[24:27]
	v_mfma_f32_16x16x32_bf16 v[20:23], v[132:135], v[198:201], v[20:23]
	v_mfma_f32_16x16x32_bf16 v[8:11], v[140:143], v[198:201], v[8:11]

	s_barrier
	s_add_i32 s63, s53, s42
	s_mov_b32 m0, s63
	s_add_u32 s64, s36, 0x80000
	s_addc_u32 s65, s37, 0


	global_load_lds_dwordx4 v172, s[64:65]
	s_add_i32 m0, s63, 0x2000
	s_nop 0

	global_load_lds_dwordx4 v174, s[64:65]
	s_waitcnt vmcnt(6)
	s_barrier

	v_mfma_f32_16x16x32_bf16 v[48:51], v[202:205], v[144:147], v[48:51]
	v_mfma_f32_16x16x32_bf16 v[44:47], v[222:225], v[144:147], v[44:47]
	v_mfma_f32_16x16x32_bf16 v[32:35], v[202:205], v[152:155], v[32:35]
	v_mfma_f32_16x16x32_bf16 v[28:31], v[222:225], v[152:155], v[28:31]
	v_mfma_f32_16x16x32_bf16 v[16:19], v[202:205], v[180:183], v[16:19]
	v_mfma_f32_16x16x32_bf16 v[12:15], v[222:225], v[180:183], v[12:15]
	v_mfma_f32_16x16x32_bf16 v[4:7], v[202:205], v[194:197], v[4:7]
	v_mfma_f32_16x16x32_bf16 v[0:3], v[222:225], v[194:197], v[0:3]
	v_mfma_f32_16x16x32_bf16 v[48:51], v[206:209], v[148:151], v[48:51]
	v_mfma_f32_16x16x32_bf16 v[44:47], v[226:229], v[148:151], v[44:47]
	v_mfma_f32_16x16x32_bf16 v[32:35], v[206:209], v[156:159], v[32:35]
	v_mfma_f32_16x16x32_bf16 v[28:31], v[226:229], v[156:159], v[28:31]
	v_mfma_f32_16x16x32_bf16 v[16:19], v[206:209], v[184:187], v[16:19]
	v_mfma_f32_16x16x32_bf16 v[12:15], v[226:229], v[184:187], v[12:15]
	v_mfma_f32_16x16x32_bf16 v[4:7], v[206:209], v[198:201], v[4:7]
	v_mfma_f32_16x16x32_bf16 v[0:3], v[226:229], v[198:201], v[0:3]

	s_add_i32 s63, 0, 0x18000
	v_add_u32_e32 v140, s63, v177
	s_barrier
	ds_read_b128 v[128:131], v140
	ds_read_b128 v[132:135], v140 offset:1024
	ds_read_b128 v[136:139], v140 offset:2048
	ds_read_b128 v[140:143], v140 offset:3072
	s_add_u32 s38, s38, 0x80000
	s_addc_u32 s39, s39, 0
	s_mov_b32 m0, s43

	ds_read_b128 v[144:147], v190 offset:32768
	ds_read_b128 v[148:151], v190 offset:33792
	ds_read_b128 v[152:155], v190 offset:34816
	ds_read_b128 v[156:159], v190 offset:35840
	ds_read_b128 v[180:183], v190 offset:36864
	ds_read_b128 v[184:187], v190 offset:37888
	ds_read_b128 v[194:197], v190 offset:38912

	global_load_lds_dwordx4 v172, s[38:39]
	s_mov_b32 m0, s44
	ds_read_b128 v[198:201], v190 offset:39936

	global_load_lds_dwordx4 v174, s[38:39]
	s_waitcnt lgkmcnt(8)
	s_barrier
	s_waitcnt lgkmcnt(0)


	v_mfma_f32_16x16x32_bf16 v[124:127], v[128:131], v[144:147], v[124:127]
	v_mfma_f32_16x16x32_bf16 v[120:123], v[136:139], v[144:147], v[120:123]
	v_mfma_f32_16x16x32_bf16 v[116:119], v[128:131], v[152:155], v[116:119]
	v_mfma_f32_16x16x32_bf16 v[104:107], v[136:139], v[152:155], v[104:107]
	v_mfma_f32_16x16x32_bf16 v[96:99], v[128:131], v[180:183], v[96:99]
	v_mfma_f32_16x16x32_bf16 v[88:91], v[136:139], v[180:183], v[88:91]
	v_mfma_f32_16x16x32_bf16 v[80:83], v[128:131], v[194:197], v[80:83]
	v_mfma_f32_16x16x32_bf16 v[72:75], v[136:139], v[194:197], v[72:75]
	v_mfma_f32_16x16x32_bf16 v[124:127], v[132:135], v[148:151], v[124:127]
	v_mfma_f32_16x16x32_bf16 v[120:123], v[140:143], v[148:151], v[120:123]
	v_mfma_f32_16x16x32_bf16 v[116:119], v[132:135], v[156:159], v[116:119]
	v_mfma_f32_16x16x32_bf16 v[104:107], v[140:143], v[156:159], v[104:107]
	v_mfma_f32_16x16x32_bf16 v[96:99], v[132:135], v[184:187], v[96:99]
	v_mfma_f32_16x16x32_bf16 v[88:91], v[140:143], v[184:187], v[88:91]
	v_mfma_f32_16x16x32_bf16 v[80:83], v[132:135], v[198:201], v[80:83]
	v_mfma_f32_16x16x32_bf16 v[72:75], v[140:143], v[198:201], v[72:75]

	s_barrier
	s_add_i32 s38, 0, 0x1c000
	s_add_i32 s39, s63, s42
	v_add_u32_e32 v160, s38, v177

	s_mov_b32 m0, s39
	ds_read_b128 v[202:205], v160
	ds_read_b128 v[206:209], v160 offset:1024
	ds_read_b128 v[222:225], v160 offset:2048

	global_load_lds_dwordx4 v172, s[66:67]
	s_add_i32 m0, s39, 0x2000
	ds_read_b128 v[226:229], v160 offset:3072

	global_load_lds_dwordx4 v174, s[66:67]
	s_barrier
	s_waitcnt lgkmcnt(0)


	v_mfma_f32_16x16x32_bf16 v[112:115], v[202:205], v[144:147], v[112:115]
	v_mfma_f32_16x16x32_bf16 v[108:111], v[222:225], v[144:147], v[108:111]
	v_mfma_f32_16x16x32_bf16 v[100:103], v[202:205], v[152:155], v[100:103]
	v_mfma_f32_16x16x32_bf16 v[92:95], v[222:225], v[152:155], v[92:95]
	v_mfma_f32_16x16x32_bf16 v[84:87], v[202:205], v[180:183], v[84:87]
	v_mfma_f32_16x16x32_bf16 v[76:79], v[222:225], v[180:183], v[76:79]
	v_mfma_f32_16x16x32_bf16 v[68:71], v[202:205], v[194:197], v[68:71]
	v_mfma_f32_16x16x32_bf16 v[64:67], v[222:225], v[194:197], v[64:67]
	v_mfma_f32_16x16x32_bf16 v[112:115], v[206:209], v[148:151], v[112:115]
	v_mfma_f32_16x16x32_bf16 v[108:111], v[226:229], v[148:151], v[108:111]
	v_mfma_f32_16x16x32_bf16 v[100:103], v[206:209], v[156:159], v[100:103]
	v_mfma_f32_16x16x32_bf16 v[92:95], v[226:229], v[156:159], v[92:95]
	v_mfma_f32_16x16x32_bf16 v[84:87], v[206:209], v[184:187], v[84:87]
	v_mfma_f32_16x16x32_bf16 v[76:79], v[226:229], v[184:187], v[76:79]
	v_mfma_f32_16x16x32_bf16 v[68:71], v[206:209], v[198:201], v[68:71]
	v_mfma_f32_16x16x32_bf16 v[64:67], v[226:229], v[198:201], v[64:67]

	s_mov_b32 m0, s48

	s_barrier
	ds_read_b128 v[144:147], v190 offset:49152
	ds_read_b128 v[148:151], v190 offset:50176
	ds_read_b128 v[152:155], v190 offset:51200
	ds_read_b128 v[156:159], v190 offset:52224
	ds_read_b128 v[180:183], v190 offset:53248
	ds_read_b128 v[184:187], v190 offset:54272
	ds_read_b128 v[194:197], v190 offset:55296

	global_load_lds_dwordx4 v172, s[68:69]
	s_mov_b32 m0, s49
	ds_read_b128 v[198:201], v190 offset:56320

	global_load_lds_dwordx4 v174, s[68:69]
	s_barrier
	s_waitcnt lgkmcnt(0)


	v_mfma_f32_16x16x32_bf16 v[60:63], v[128:131], v[144:147], v[60:63]
	v_mfma_f32_16x16x32_bf16 v[56:59], v[136:139], v[144:147], v[56:59]
	v_mfma_f32_16x16x32_bf16 v[52:55], v[128:131], v[152:155], v[52:55]
	v_mfma_f32_16x16x32_bf16 v[40:43], v[136:139], v[152:155], v[40:43]
	v_mfma_f32_16x16x32_bf16 v[36:39], v[128:131], v[180:183], v[36:39]
	v_mfma_f32_16x16x32_bf16 v[24:27], v[136:139], v[180:183], v[24:27]
	v_mfma_f32_16x16x32_bf16 v[20:23], v[128:131], v[194:197], v[20:23]
	v_mfma_f32_16x16x32_bf16 v[8:11], v[136:139], v[194:197], v[8:11]
	v_mfma_f32_16x16x32_bf16 v[60:63], v[132:135], v[148:151], v[60:63]
	v_mfma_f32_16x16x32_bf16 v[56:59], v[140:143], v[148:151], v[56:59]
	v_mfma_f32_16x16x32_bf16 v[52:55], v[132:135], v[156:159], v[52:55]
	v_mfma_f32_16x16x32_bf16 v[40:43], v[140:143], v[156:159], v[40:43]
	v_mfma_f32_16x16x32_bf16 v[36:39], v[132:135], v[184:187], v[36:39]
	v_mfma_f32_16x16x32_bf16 v[24:27], v[140:143], v[184:187], v[24:27]
	v_mfma_f32_16x16x32_bf16 v[20:23], v[132:135], v[198:201], v[20:23]
	v_mfma_f32_16x16x32_bf16 v[8:11], v[140:143], v[198:201], v[8:11]

	s_barrier
	s_add_i32 s38, s38, s42
	s_mov_b32 m0, s38
	s_add_u32 s36, s36, 0x80080
	s_addc_u32 s37, s37, 0


	global_load_lds_dwordx4 v172, s[36:37]
	s_add_i32 m0, s38, 0x2000
	s_nop 0

	global_load_lds_dwordx4 v174, s[36:37]
	s_waitcnt vmcnt(6)
	s_barrier

	v_mfma_f32_16x16x32_bf16 v[48:51], v[202:205], v[144:147], v[48:51]
	v_mfma_f32_16x16x32_bf16 v[44:47], v[222:225], v[144:147], v[44:47]
	v_mfma_f32_16x16x32_bf16 v[32:35], v[202:205], v[152:155], v[32:35]
	v_mfma_f32_16x16x32_bf16 v[28:31], v[222:225], v[152:155], v[28:31]
	v_mfma_f32_16x16x32_bf16 v[16:19], v[202:205], v[180:183], v[16:19]
	v_mfma_f32_16x16x32_bf16 v[12:15], v[222:225], v[180:183], v[12:15]
	v_mfma_f32_16x16x32_bf16 v[4:7], v[202:205], v[194:197], v[4:7]
	v_mfma_f32_16x16x32_bf16 v[0:3], v[222:225], v[194:197], v[0:3]
	v_mfma_f32_16x16x32_bf16 v[48:51], v[206:209], v[148:151], v[48:51]
	v_mfma_f32_16x16x32_bf16 v[44:47], v[226:229], v[148:151], v[44:47]
	v_mfma_f32_16x16x32_bf16 v[32:35], v[206:209], v[156:159], v[32:35]
	v_mfma_f32_16x16x32_bf16 v[28:31], v[226:229], v[156:159], v[28:31]
	v_mfma_f32_16x16x32_bf16 v[16:19], v[206:209], v[184:187], v[16:19]
	v_mfma_f32_16x16x32_bf16 v[12:15], v[226:229], v[184:187], v[12:15]
	v_mfma_f32_16x16x32_bf16 v[4:7], v[206:209], v[198:201], v[4:7]
	v_mfma_f32_16x16x32_bf16 v[0:3], v[226:229], v[198:201], v[0:3]

	s_add_u32 s4, s4, 0x100
	s_addc_u32 s5, s5, 0
	s_add_u32 s60, s60, 0x100
	s_addc_u32 s61, s61, 0
	s_cmp_ge_i32 s62, s17
	s_mov_b32 s36, s62
	s_barrier
	s_cbranch_scc0 .LBB0_1024
	v_mov_b32_e32 v128, v210
	v_mov_b32_e32 v129, v169
	s_cmp_lt_i32 s12, 0
	v_lshl_add_u32 v128, v128, 4, v129
	v_ashrrev_i32_e32 v166, 2, v128
	v_and_b32_e32 v160, 3, v129
	v_and_b32_e32 v128, -4, v128
	v_lshl_add_u32 v193, v160, 6, v128
	s_mov_b64 s[4:5], -1
	s_cbranch_scc0 .LBB0_1043
	s_lshl_b32 s4, s30, 8
	v_lshl_or_b32 v128, v160, 2, s4
	s_lshl_b32 s4, s34, 8
	v_or_b32_e32 v180, s47, v128
	s_add_i32 s4, s4, s46
	v_readlane_b32 s60, v254, 6
	v_ashrrev_i32_e32 v181, 31, v180
	v_add_u32_e32 v184, s4, v166
	s_cmp_lt_i32 s34, 32
	v_readlane_b32 s61, v254, 7
	v_lshlrev_b64 v[128:129], 2, v[180:181]
	v_readlane_b32 s62, v254, 8
	v_readlane_b32 s63, v254, 9
	v_readlane_b32 s64, v254, 10
	v_readlane_b32 s65, v254, 11
	v_readlane_b32 s66, v254, 12
	v_readlane_b32 s67, v254, 13
	v_readlane_b32 s68, v254, 14
	v_readlane_b32 s69, v254, 15
	v_readlane_b32 s70, v254, 16
	v_readlane_b32 s71, v254, 17
	v_readlane_b32 s72, v254, 18
	v_readlane_b32 s73, v254, 19
	v_readlane_b32 s74, v254, 20
	v_readlane_b32 s75, v254, 21
	s_cselect_b32 s5, s61, s51
	s_cselect_b32 s4, s60, s50
	v_ashrrev_i32_e32 v185, 31, v184
	v_lshl_add_u64 v[182:183], s[4:5], 0, v[128:129]
	v_lshlrev_b64 v[130:131], 13, v[184:185]
	v_readlane_b32 s60, v254, 22
	v_lshl_add_u64 v[136:137], v[182:183], 0, v[130:131]
	v_readlane_b32 s61, v254, 23
	v_readlane_b32 s68, v254, 30
	v_readlane_b32 s69, v254, 31
	global_load_dwordx4 v[196:199], v[136:137], off nt
	global_load_dwordx4 v[200:203], v[136:137], off offset:64 nt
	global_load_dwordx4 v[204:207], v[136:137], off offset:512 nt
	s_mov_b64 s[60:61], s[68:69]
	v_lshl_add_u64 v[138:139], s[60:61], 0, v[128:129]
	global_load_dwordx4 v[140:143], v[138:139], off
	global_load_dwordx4 v[132:135], v[138:139], off offset:64
	global_load_dwordx4 v[128:131], v[138:139], off offset:512
	global_load_dwordx4 v[222:225], v[136:137], off offset:576 nt
	v_and_b32_e32 v145, 64, v192
	global_load_dwordx4 v[136:139], v[138:139], off offset:576
	v_xor_b32_e32 v144, 1, v192
	v_add_u32_e32 v194, 64, v145
	v_add_u32_e32 v186, 16, v184
	v_cmp_lt_i32_e64 s[4:5], v144, v194
	v_ashrrev_i32_e32 v187, 31, v186
	ds_bpermute_b32 v188, v193, v124
	v_cndmask_b32_e64 v195, v192, v144, s[4:5]
	v_lshlrev_b64 v[144:145], 13, v[186:187]
	v_lshl_add_u64 v[144:145], v[182:183], 0, v[144:145]
	global_load_dwordx4 v[156:159], v[144:145], off nt
	global_load_dwordx4 v[152:155], v[144:145], off offset:64 nt
	global_load_dwordx4 v[148:151], v[144:145], off offset:512 nt
	s_nop 0
	global_load_dwordx4 v[144:147], v[144:145], off offset:576 nt
	ds_bpermute_b32 v189, v193, v125
	ds_bpermute_b32 v208, v193, v126
	ds_bpermute_b32 v209, v193, v127
	ds_bpermute_b32 v226, v193, v120
	ds_bpermute_b32 v227, v193, v121
	ds_bpermute_b32 v228, v193, v122
	ds_bpermute_b32 v229, v193, v123
	ds_bpermute_b32 v230, v193, v112
	ds_bpermute_b32 v231, v193, v113
	v_readlane_b32 s64, v254, 26
	v_readlane_b32 s65, v254, 27
	v_readlane_b32 s66, v254, 28
	v_readlane_b32 s67, v254, 29
	v_readlane_b32 s72, v254, 34
	v_readlane_b32 s73, v254, 35
	v_readlane_b32 s74, v254, 36
	v_readlane_b32 s75, v254, 37
	s_mov_b64 s[64:65], s[72:73]
	ds_bpermute_b32 v232, v193, v114
	ds_bpermute_b32 v233, v193, v115
	v_lshlrev_b64 v[234:235], 11, v[184:185]
	s_mov_b64 s[66:67], s[74:75]
	v_lshl_add_u64 v[234:235], v[234:235], 0, v[180:181]
	v_xor_b32_e32 v167, 2, v192
	v_lshl_add_u64 v[236:237], v[234:235], 2, s[66:67]
	v_readlane_b32 s2, v254, 54
	v_cmp_lt_i32_e64 s[4:5], v167, v194
	v_lshlrev_b32_e32 v194, 2, v195
	v_lshlrev_b64 v[234:235], 1, v[234:235]
	v_readlane_b32 s3, v254, 55
	v_or_b32_e32 v240, 32, v234
	v_mov_b32_e32 v241, v235
	v_lshl_add_u64 v[238:239], s[2:3], 0, v[234:235]
	v_lshl_add_u64 v[240:241], s[2:3], 0, v[240:241]
	v_cndmask_b32_e64 v167, v192, v167, s[4:5]
	v_lshlrev_b32_e32 v167, 2, v167
	v_cmp_eq_u32_e32 vcc, 0, v160
	v_readlane_b32 s62, v254, 24
	v_readlane_b32 s63, v254, 25
	v_readlane_b32 s70, v254, 32
	v_readlane_b32 s71, v254, 33
	s_waitcnt vmcnt(0) lgkmcnt(0)
	v_pk_add_f32 v[198:199], v[198:199], v[208:209]
	v_pk_add_f32 v[196:197], v[196:197], v[188:189]
	v_pk_add_f32 v[202:203], v[202:203], v[228:229]
	v_pk_add_f32 v[200:201], v[200:201], v[226:227]
	v_pk_add_f32 v[204:205], v[204:205], v[230:231]
	v_mul_f32_e32 v195, v197, v197
	v_mul_f32_e32 v221, v199, v199
	global_store_dwordx4 v[236:237], v[196:199], off
	v_pk_mul_f32 v[188:189], v[142:143], v[198:199]
	v_pk_mul_f32 v[208:209], v[140:141], v[196:197]
	v_mul_f32_e32 v199, v201, v201
	v_mul_f32_e32 v230, v203, v203
	v_pk_mul_f32 v[226:227], v[134:135], v[202:203]
	v_pk_mul_f32 v[228:229], v[132:133], v[200:201]
	v_fmac_f32_e32 v195, v196, v196
	v_fmac_f32_e32 v221, v198, v198
	v_cvt_pk_bf16_f32 v196, v208, v209
	v_cvt_pk_bf16_f32 v197, v188, v189
	v_fmac_f32_e32 v199, v200, v200
	v_fmac_f32_e32 v230, v202, v202
	v_pk_add_f32 v[206:207], v[206:207], v[232:233]
	v_cvt_pk_bf16_f32 v188, v228, v229
	v_cvt_pk_bf16_f32 v189, v226, v227
	v_add_f32_e32 v195, v195, v221
	global_store_dwordx2 v[238:239], v[196:197], off
	v_add_f32_e32 v196, v199, v230
	global_store_dwordx4 v[236:237], v[200:203], off offset:64
	global_store_dwordx2 v[240:241], v[188:189], off
	v_add_f32_e32 v188, v195, v196
	v_mul_f32_e32 v189, v205, v205
	v_mul_f32_e32 v195, v207, v207
	v_fmac_f32_e32 v189, v204, v204
	v_fmac_f32_e32 v195, v206, v206
	ds_bpermute_b32 v200, v193, v108
	ds_bpermute_b32 v198, v193, v110
	ds_bpermute_b32 v199, v193, v111
	ds_bpermute_b32 v201, v193, v109
	v_add_f32_e32 v189, v189, v195
	v_add_f32_e32 v195, v188, v189
	v_pk_mul_f32 v[188:189], v[130:131], v[206:207]
	v_pk_mul_f32 v[196:197], v[128:129], v[204:205]
	global_store_dwordx4 v[236:237], v[204:207], off offset:512
	v_cvt_pk_bf16_f32 v196, v196, v197
	v_cvt_pk_bf16_f32 v197, v188, v189
	v_or_b32_e32 v188, 0x100, v234
	v_mov_b32_e32 v189, v235
	v_lshl_add_u64 v[188:189], s[2:3], 0, v[188:189]
	global_store_dwordx2 v[188:189], v[196:197], off
	s_waitcnt lgkmcnt(1)
	v_pk_add_f32 v[198:199], v[224:225], v[198:199]
	s_waitcnt lgkmcnt(0)
	v_pk_add_f32 v[196:197], v[222:223], v[200:201]
	v_mul_f32_e32 v189, v199, v199
	v_mul_f32_e32 v188, v197, v197
	v_fmac_f32_e32 v188, v196, v196
	v_fmac_f32_e32 v189, v198, v198
	v_add_f32_e32 v188, v188, v189
	v_add_f32_e32 v195, v195, v188
	ds_bpermute_b32 v200, v194, v195
	v_pk_mul_f32 v[188:189], v[136:137], v[196:197]
	global_store_dwordx4 v[236:237], v[196:199], off offset:576
	v_or_b32_e32 v234, 0x120, v234
	s_nop 0
	v_cvt_pk_bf16_f32 v196, v188, v189
	s_waitcnt lgkmcnt(0)
	v_add_f32_e32 v188, v195, v200
	ds_bpermute_b32 v189, v167, v188
	v_pk_mul_f32 v[198:199], v[138:139], v[198:199]
	s_nop 0
	v_cvt_pk_bf16_f32 v197, v198, v199
	v_lshl_add_u64 v[198:199], s[2:3], 0, v[234:235]
	global_store_dwordx2 v[198:199], v[196:197], off
	s_and_saveexec_b64 s[4:5], vcc
	s_cbranch_execz .LBB0_1028
	s_waitcnt lgkmcnt(0)
	v_add_f32_e32 v195, v188, v189
	s_lshl_b32 s36, s30, 2
	v_lshlrev_b64 v[188:189], 7, v[184:185]
	s_ashr_i32 s37, s36, 31
	v_lshl_add_u64 v[188:189], s[10:11], 0, v[188:189]
	v_lshl_add_u64 v[188:189], s[36:37], 2, v[188:189]
	s_lshl_b32 s36, s45, 2
	s_mov_b32 s37, s13
	v_lshl_add_u64 v[188:189], v[188:189], 0, s[36:37]
	global_store_dword v[188:189], v195, off

.LBB0_1167:
	ds_read_b128 v[148:151], v143
	ds_read_b128 v[152:155], v143 offset:1024
	ds_read_b128 v[156:159], v143 offset:2048
	ds_read_b128 v[160:163], v143 offset:3072
	s_add_u32 s24, s22, 0xfff80080
	s_addc_u32 s25, s23, -1
	s_cmp_eq_u32 s53, 28
	s_cselect_b32 s27, s15, s25
	s_cselect_b32 s26, s49, s24
	s_cselect_b32 s25, s13, s52
	s_cselect_b32 s24, s50, s51

	s_add_i32 m0, s21, 0xc000
	ds_read_b128 v[164:167], v145
	ds_read_b128 v[176:179], v145 offset:1024
	ds_read_b128 v[180:183], v145 offset:2048
	ds_read_b128 v[184:187], v145 offset:3072
	ds_read_b128 v[188:191], v145 offset:4096
	ds_read_b128 v[192:195], v145 offset:5120
	ds_read_b128 v[196:199], v145 offset:6144

	global_load_lds_dwordx4 v128, s[22:23]
	s_add_i32 m0, s21, 0xe000
	ds_read_b128 v[200:203], v145 offset:7168

	global_load_lds_dwordx4 v130, s[22:23]
	s_waitcnt lgkmcnt(8)
	s_barrier
	s_waitcnt lgkmcnt(0)


	v_mfma_f32_16x16x32_bf16 v[124:127], v[148:151], v[164:167], v[124:127]
	v_mfma_f32_16x16x32_bf16 v[120:123], v[156:159], v[164:167], v[120:123]
	v_mfma_f32_16x16x32_bf16 v[116:119], v[148:151], v[180:183], v[116:119]
	v_mfma_f32_16x16x32_bf16 v[104:107], v[156:159], v[180:183], v[104:107]
	v_mfma_f32_16x16x32_bf16 v[96:99], v[148:151], v[188:191], v[96:99]
	v_mfma_f32_16x16x32_bf16 v[88:91], v[156:159], v[188:191], v[88:91]
	v_mfma_f32_16x16x32_bf16 v[80:83], v[148:151], v[196:199], v[80:83]
	v_mfma_f32_16x16x32_bf16 v[72:75], v[156:159], v[196:199], v[72:75]
	v_mfma_f32_16x16x32_bf16 v[124:127], v[152:155], v[176:179], v[124:127]
	v_mfma_f32_16x16x32_bf16 v[120:123], v[160:163], v[176:179], v[120:123]
	v_mfma_f32_16x16x32_bf16 v[116:119], v[152:155], v[184:187], v[116:119]
	v_mfma_f32_16x16x32_bf16 v[104:107], v[160:163], v[184:187], v[104:107]
	v_mfma_f32_16x16x32_bf16 v[96:99], v[152:155], v[192:195], v[96:99]
	v_mfma_f32_16x16x32_bf16 v[88:91], v[160:163], v[192:195], v[88:91]
	v_mfma_f32_16x16x32_bf16 v[80:83], v[152:155], v[200:203], v[80:83]
	v_mfma_f32_16x16x32_bf16 v[72:75], v[160:163], v[200:203], v[72:75]

	s_barrier
	s_add_i32 s54, s45, s31
	s_add_u32 s66, s24, s10
	s_addc_u32 s67, s25, s11
	s_mov_b32 m0, s54
	ds_read_b128 v[204:207], v147
	ds_read_b128 v[218:221], v147 offset:1024
	ds_read_b128 v[222:225], v147 offset:2048

	global_load_lds_dwordx4 v172, s[24:25]
	s_add_i32 m0, s54, 0x2000
	ds_read_b128 v[226:229], v147 offset:3072

	global_load_lds_dwordx4 v174, s[24:25]
	s_barrier
	s_waitcnt lgkmcnt(0)


	v_mfma_f32_16x16x32_bf16 v[112:115], v[204:207], v[164:167], v[112:115]
	v_mfma_f32_16x16x32_bf16 v[108:111], v[222:225], v[164:167], v[108:111]
	v_mfma_f32_16x16x32_bf16 v[100:103], v[204:207], v[180:183], v[100:103]
	v_mfma_f32_16x16x32_bf16 v[92:95], v[222:225], v[180:183], v[92:95]
	v_mfma_f32_16x16x32_bf16 v[84:87], v[204:207], v[188:191], v[84:87]
	v_mfma_f32_16x16x32_bf16 v[76:79], v[222:225], v[188:191], v[76:79]
	v_mfma_f32_16x16x32_bf16 v[68:71], v[204:207], v[196:199], v[68:71]
	v_mfma_f32_16x16x32_bf16 v[64:67], v[222:225], v[196:199], v[64:67]
	v_mfma_f32_16x16x32_bf16 v[112:115], v[218:221], v[176:179], v[112:115]
	v_mfma_f32_16x16x32_bf16 v[108:111], v[226:229], v[176:179], v[108:111]
	v_mfma_f32_16x16x32_bf16 v[100:103], v[218:221], v[184:187], v[100:103]
	v_mfma_f32_16x16x32_bf16 v[92:95], v[226:229], v[184:187], v[92:95]
	v_mfma_f32_16x16x32_bf16 v[84:87], v[218:221], v[192:195], v[84:87]
	v_mfma_f32_16x16x32_bf16 v[76:79], v[226:229], v[192:195], v[76:79]
	v_mfma_f32_16x16x32_bf16 v[68:71], v[218:221], v[200:203], v[68:71]
	v_mfma_f32_16x16x32_bf16 v[64:67], v[226:229], v[200:203], v[64:67]

	s_mov_b32 m0, s21
	s_add_u32 s68, s26, s10
	s_addc_u32 s69, s27, s11
	s_barrier
	ds_read_b128 v[164:167], v145 offset:16384
	ds_read_b128 v[176:179], v145 offset:17408
	ds_read_b128 v[180:183], v145 offset:18432
	ds_read_b128 v[184:187], v145 offset:19456
	ds_read_b128 v[188:191], v145 offset:20480
	ds_read_b128 v[192:195], v145 offset:21504
	ds_read_b128 v[196:199], v145 offset:22528

	global_load_lds_dwordx4 v172, s[26:27]
	s_mov_b32 m0, s35
	ds_read_b128 v[200:203], v145 offset:23552

	global_load_lds_dwordx4 v174, s[26:27]
	s_barrier
	s_waitcnt lgkmcnt(0)


	v_mfma_f32_16x16x32_bf16 v[60:63], v[148:151], v[164:167], v[60:63]
	v_mfma_f32_16x16x32_bf16 v[56:59], v[156:159], v[164:167], v[56:59]
	v_mfma_f32_16x16x32_bf16 v[48:51], v[148:151], v[180:183], v[48:51]
	v_mfma_f32_16x16x32_bf16 v[40:43], v[156:159], v[180:183], v[40:43]
	v_mfma_f32_16x16x32_bf16 v[32:35], v[148:151], v[188:191], v[32:35]
	v_mfma_f32_16x16x32_bf16 v[24:27], v[156:159], v[188:191], v[24:27]
	v_mfma_f32_16x16x32_bf16 v[16:19], v[148:151], v[196:199], v[16:19]
	v_mfma_f32_16x16x32_bf16 v[8:11], v[156:159], v[196:199], v[8:11]
	v_mfma_f32_16x16x32_bf16 v[60:63], v[152:155], v[176:179], v[60:63]
	v_mfma_f32_16x16x32_bf16 v[56:59], v[160:163], v[176:179], v[56:59]
	v_mfma_f32_16x16x32_bf16 v[48:51], v[152:155], v[184:187], v[48:51]
	v_mfma_f32_16x16x32_bf16 v[40:43], v[160:163], v[184:187], v[40:43]
	v_mfma_f32_16x16x32_bf16 v[32:35], v[152:155], v[192:195], v[32:35]
	v_mfma_f32_16x16x32_bf16 v[24:27], v[160:163], v[192:195], v[24:27]
	v_mfma_f32_16x16x32_bf16 v[16:19], v[152:155], v[200:203], v[16:19]
	v_mfma_f32_16x16x32_bf16 v[8:11], v[160:163], v[200:203], v[8:11]

	s_barrier
	s_add_i32 s56, s46, s31
	s_mov_b32 m0, s56
	s_add_u32 s54, s24, 0x80000
	s_addc_u32 s55, s25, 0


	global_load_lds_dwordx4 v172, s[54:55]
	s_add_i32 m0, s56, 0x2000
	s_nop 0

	global_load_lds_dwordx4 v174, s[54:55]
	s_waitcnt vmcnt(6)
	s_barrier

	v_mfma_f32_16x16x32_bf16 v[52:55], v[204:207], v[164:167], v[52:55]
	v_mfma_f32_16x16x32_bf16 v[44:47], v[222:225], v[164:167], v[44:47]
	v_mfma_f32_16x16x32_bf16 v[36:39], v[204:207], v[180:183], v[36:39]
	v_mfma_f32_16x16x32_bf16 v[28:31], v[222:225], v[180:183], v[28:31]
	v_mfma_f32_16x16x32_bf16 v[20:23], v[204:207], v[188:191], v[20:23]
	v_mfma_f32_16x16x32_bf16 v[12:15], v[222:225], v[188:191], v[12:15]
	v_mfma_f32_16x16x32_bf16 v[4:7], v[204:207], v[196:199], v[4:7]
	v_mfma_f32_16x16x32_bf16 v[0:3], v[222:225], v[196:199], v[0:3]
	v_mfma_f32_16x16x32_bf16 v[52:55], v[218:221], v[176:179], v[52:55]
	v_mfma_f32_16x16x32_bf16 v[44:47], v[226:229], v[176:179], v[44:47]
	v_mfma_f32_16x16x32_bf16 v[36:39], v[218:221], v[184:187], v[36:39]
	v_mfma_f32_16x16x32_bf16 v[28:31], v[226:229], v[184:187], v[28:31]
	v_mfma_f32_16x16x32_bf16 v[20:23], v[218:221], v[192:195], v[20:23]
	v_mfma_f32_16x16x32_bf16 v[12:15], v[226:229], v[192:195], v[12:15]
	v_mfma_f32_16x16x32_bf16 v[4:7], v[218:221], v[200:203], v[4:7]
	v_mfma_f32_16x16x32_bf16 v[0:3], v[226:229], v[200:203], v[0:3]

	s_add_i32 s54, 0, 0x18000
	v_add_u32_e32 v138, s54, v139
	s_barrier
	ds_read_b128 v[148:151], v138
	ds_read_b128 v[152:155], v138 offset:1024
	ds_read_b128 v[156:159], v138 offset:2048
	ds_read_b128 v[160:163], v138 offset:3072
	s_add_u32 s26, s26, 0x80000
	s_addc_u32 s27, s27, 0
	s_mov_b32 m0, s36

	ds_read_b128 v[164:167], v145 offset:32768
	ds_read_b128 v[176:179], v145 offset:33792
	ds_read_b128 v[180:183], v145 offset:34816
	ds_read_b128 v[184:187], v145 offset:35840
	ds_read_b128 v[188:191], v145 offset:36864
	ds_read_b128 v[192:195], v145 offset:37888
	ds_read_b128 v[196:199], v145 offset:38912

	global_load_lds_dwordx4 v172, s[26:27]
	s_mov_b32 m0, s37
	ds_read_b128 v[200:203], v145 offset:39936

	global_load_lds_dwordx4 v174, s[26:27]
	s_waitcnt lgkmcnt(8)
	s_barrier
	s_waitcnt lgkmcnt(0)


	v_mfma_f32_16x16x32_bf16 v[124:127], v[148:151], v[164:167], v[124:127]
	v_mfma_f32_16x16x32_bf16 v[120:123], v[156:159], v[164:167], v[120:123]
	v_mfma_f32_16x16x32_bf16 v[116:119], v[148:151], v[180:183], v[116:119]
	v_mfma_f32_16x16x32_bf16 v[104:107], v[156:159], v[180:183], v[104:107]
	v_mfma_f32_16x16x32_bf16 v[96:99], v[148:151], v[188:191], v[96:99]
	v_mfma_f32_16x16x32_bf16 v[88:91], v[156:159], v[188:191], v[88:91]
	v_mfma_f32_16x16x32_bf16 v[80:83], v[148:151], v[196:199], v[80:83]
	v_mfma_f32_16x16x32_bf16 v[72:75], v[156:159], v[196:199], v[72:75]
	v_mfma_f32_16x16x32_bf16 v[124:127], v[152:155], v[176:179], v[124:127]
	v_mfma_f32_16x16x32_bf16 v[120:123], v[160:163], v[176:179], v[120:123]
	v_mfma_f32_16x16x32_bf16 v[116:119], v[152:155], v[184:187], v[116:119]
	v_mfma_f32_16x16x32_bf16 v[104:107], v[160:163], v[184:187], v[104:107]
	v_mfma_f32_16x16x32_bf16 v[96:99], v[152:155], v[192:195], v[96:99]
	v_mfma_f32_16x16x32_bf16 v[88:91], v[160:163], v[192:195], v[88:91]
	v_mfma_f32_16x16x32_bf16 v[80:83], v[152:155], v[200:203], v[80:83]
	v_mfma_f32_16x16x32_bf16 v[72:75], v[160:163], v[200:203], v[72:75]

	s_barrier
	s_add_i32 s26, 0, 0x1c000
	s_add_i32 s27, s54, s31
	v_add_u32_e32 v138, s26, v139

	s_mov_b32 m0, s27
	ds_read_b128 v[204:207], v138
	ds_read_b128 v[218:221], v138 offset:1024
	ds_read_b128 v[222:225], v138 offset:2048

	global_load_lds_dwordx4 v172, s[66:67]
	s_add_i32 m0, s27, 0x2000
	ds_read_b128 v[226:229], v138 offset:3072

	global_load_lds_dwordx4 v174, s[66:67]
	s_barrier
	s_waitcnt lgkmcnt(0)


	v_mfma_f32_16x16x32_bf16 v[112:115], v[204:207], v[164:167], v[112:115]
	v_mfma_f32_16x16x32_bf16 v[108:111], v[222:225], v[164:167], v[108:111]
	v_mfma_f32_16x16x32_bf16 v[100:103], v[204:207], v[180:183], v[100:103]
	v_mfma_f32_16x16x32_bf16 v[92:95], v[222:225], v[180:183], v[92:95]
	v_mfma_f32_16x16x32_bf16 v[84:87], v[204:207], v[188:191], v[84:87]
	v_mfma_f32_16x16x32_bf16 v[76:79], v[222:225], v[188:191], v[76:79]
	v_mfma_f32_16x16x32_bf16 v[68:71], v[204:207], v[196:199], v[68:71]
	v_mfma_f32_16x16x32_bf16 v[64:67], v[222:225], v[196:199], v[64:67]
	v_mfma_f32_16x16x32_bf16 v[112:115], v[218:221], v[176:179], v[112:115]
	v_mfma_f32_16x16x32_bf16 v[108:111], v[226:229], v[176:179], v[108:111]
	v_mfma_f32_16x16x32_bf16 v[100:103], v[218:221], v[184:187], v[100:103]
	v_mfma_f32_16x16x32_bf16 v[92:95], v[226:229], v[184:187], v[92:95]
	v_mfma_f32_16x16x32_bf16 v[84:87], v[218:221], v[192:195], v[84:87]
	v_mfma_f32_16x16x32_bf16 v[76:79], v[226:229], v[192:195], v[76:79]
	v_mfma_f32_16x16x32_bf16 v[68:71], v[218:221], v[200:203], v[68:71]
	v_mfma_f32_16x16x32_bf16 v[64:67], v[226:229], v[200:203], v[64:67]

	s_mov_b32 m0, s41

	s_barrier
	ds_read_b128 v[164:167], v145 offset:49152
	ds_read_b128 v[176:179], v145 offset:50176
	ds_read_b128 v[180:183], v145 offset:51200
	ds_read_b128 v[184:187], v145 offset:52224
	ds_read_b128 v[188:191], v145 offset:53248
	ds_read_b128 v[192:195], v145 offset:54272
	ds_read_b128 v[196:199], v145 offset:55296

	global_load_lds_dwordx4 v172, s[68:69]
	s_mov_b32 m0, s42
	ds_read_b128 v[200:203], v145 offset:56320

	global_load_lds_dwordx4 v174, s[68:69]
	s_barrier
	s_waitcnt lgkmcnt(0)


	v_mfma_f32_16x16x32_bf16 v[60:63], v[148:151], v[164:167], v[60:63]
	v_mfma_f32_16x16x32_bf16 v[56:59], v[156:159], v[164:167], v[56:59]
	v_mfma_f32_16x16x32_bf16 v[48:51], v[148:151], v[180:183], v[48:51]
	v_mfma_f32_16x16x32_bf16 v[40:43], v[156:159], v[180:183], v[40:43]
	v_mfma_f32_16x16x32_bf16 v[32:35], v[148:151], v[188:191], v[32:35]
	v_mfma_f32_16x16x32_bf16 v[24:27], v[156:159], v[188:191], v[24:27]
	v_mfma_f32_16x16x32_bf16 v[16:19], v[148:151], v[196:199], v[16:19]
	v_mfma_f32_16x16x32_bf16 v[8:11], v[156:159], v[196:199], v[8:11]
	v_mfma_f32_16x16x32_bf16 v[60:63], v[152:155], v[176:179], v[60:63]
	v_mfma_f32_16x16x32_bf16 v[56:59], v[160:163], v[176:179], v[56:59]
	v_mfma_f32_16x16x32_bf16 v[48:51], v[152:155], v[184:187], v[48:51]
	v_mfma_f32_16x16x32_bf16 v[40:43], v[160:163], v[184:187], v[40:43]
	v_mfma_f32_16x16x32_bf16 v[32:35], v[152:155], v[192:195], v[32:35]
	v_mfma_f32_16x16x32_bf16 v[24:27], v[160:163], v[192:195], v[24:27]
	v_mfma_f32_16x16x32_bf16 v[16:19], v[152:155], v[200:203], v[16:19]
	v_mfma_f32_16x16x32_bf16 v[8:11], v[160:163], v[200:203], v[8:11]

	s_barrier
	s_add_i32 s26, s26, s31
	s_mov_b32 m0, s26
	s_add_u32 s24, s24, 0x80080
	s_addc_u32 s25, s25, 0


	global_load_lds_dwordx4 v172, s[24:25]
	s_add_i32 m0, s26, 0x2000
	s_nop 0

	global_load_lds_dwordx4 v174, s[24:25]
	s_waitcnt vmcnt(6)
	s_barrier

	v_mfma_f32_16x16x32_bf16 v[52:55], v[204:207], v[164:167], v[52:55]
	v_mfma_f32_16x16x32_bf16 v[44:47], v[222:225], v[164:167], v[44:47]
	v_mfma_f32_16x16x32_bf16 v[36:39], v[204:207], v[180:183], v[36:39]
	v_mfma_f32_16x16x32_bf16 v[28:31], v[222:225], v[180:183], v[28:31]
	v_mfma_f32_16x16x32_bf16 v[20:23], v[204:207], v[188:191], v[20:23]
	v_mfma_f32_16x16x32_bf16 v[12:15], v[222:225], v[188:191], v[12:15]
	v_mfma_f32_16x16x32_bf16 v[4:7], v[204:207], v[196:199], v[4:7]
	v_mfma_f32_16x16x32_bf16 v[0:3], v[222:225], v[196:199], v[0:3]
	v_mfma_f32_16x16x32_bf16 v[52:55], v[218:221], v[176:179], v[52:55]
	v_mfma_f32_16x16x32_bf16 v[44:47], v[226:229], v[176:179], v[44:47]
	v_mfma_f32_16x16x32_bf16 v[36:39], v[218:221], v[184:187], v[36:39]
	v_mfma_f32_16x16x32_bf16 v[28:31], v[226:229], v[184:187], v[28:31]
	v_mfma_f32_16x16x32_bf16 v[20:23], v[218:221], v[192:195], v[20:23]
	v_mfma_f32_16x16x32_bf16 v[12:15], v[226:229], v[192:195], v[12:15]
	v_mfma_f32_16x16x32_bf16 v[4:7], v[218:221], v[200:203], v[4:7]
	v_mfma_f32_16x16x32_bf16 v[0:3], v[226:229], v[200:203], v[0:3]

	s_add_i32 s53, s53, 2
	s_add_u32 s22, s22, 0x100
	s_addc_u32 s23, s23, 0
	s_add_u32 s51, s51, 0x100
	s_addc_u32 s52, s52, 0
	s_cmp_gt_u32 s53, 29
	s_barrier
	s_cbranch_scc0 .LBB0_1167
	s_lshl_b32 s13, s20, 8
	v_mov_b32_e32 v138, v210
	v_mov_b32_e32 v142, v169
	s_add_i32 s13, s13, s39
	s_lshl_b32 s15, s48, 7
	v_add_u32_e32 v136, s13, v142
	v_ashrrev_i32_e32 v137, 31, v136
	v_lshl_add_u64 v[140:141], v[136:137], 2, s[2:3]
	global_load_dword v154, v[140:141], off
	global_load_dword v152, v[140:141], off offset:64
	v_lshl_add_u32 v138, v138, 4, v142
	v_and_b32_e32 v142, 3, v142
	v_ashrrev_i32_e32 v144, 2, v138
	v_and_b32_e32 v138, -4, v138
	v_lshl_or_b32 v146, v142, 2, s15
	v_add_u32_e32 v151, s13, v144
	v_lshl_add_u32 v149, v142, 6, v138
	v_or_b32_e32 v156, s40, v146
	global_load_dword v150, v[140:141], off offset:128
	global_load_dword v148, v[140:141], off offset:192
	global_load_dword v146, v[140:141], off offset:512
	global_load_dword v144, v[140:141], off offset:576
	global_load_dword v142, v[140:141], off offset:640
	global_load_dword v138, v[140:141], off offset:704
	v_mov_b64_e32 v[136:137], s[0:1]
	v_ashrrev_i32_e32 v157, 31, v156
	v_mad_i64_i32 v[158:159], s[22:23], v151, s47, v[136:137]
	v_lshlrev_b64 v[140:141], 1, v[156:157]
	v_lshl_add_u64 v[156:157], v[158:159], 0, v[140:141]
	v_add_u32_e32 v153, 16, v151
	s_and_b64 vcc, exec, s[4:5]
	s_mov_b32 s48, s12
	s_mov_b32 s20, s14
	s_mov_b64 s[24:25], s[18:19]
	s_waitcnt vmcnt(0)
	v_pk_mul_f32 v[126:127], v[126:127], v[154:155] op_sel_hi:[1,0]
	v_pk_mul_f32 v[124:125], v[124:125], v[154:155] op_sel_hi:[1,0]
	v_pk_mul_f32 v[114:115], v[114:115], v[154:155] op_sel_hi:[1,0]
	v_pk_mul_f32 v[112:113], v[112:113], v[154:155] op_sel_hi:[1,0]
	v_pk_mul_f32 v[122:123], v[122:123], v[154:155] op_sel_hi:[1,0]
	v_pk_mul_f32 v[120:121], v[120:121], v[154:155] op_sel_hi:[1,0]
	v_pk_mul_f32 v[110:111], v[110:111], v[154:155] op_sel_hi:[1,0]
	v_pk_mul_f32 v[108:109], v[108:109], v[154:155] op_sel_hi:[1,0]
	v_mul_f32_e32 v154, 0xbfb8aa3b, v124
	v_mul_f32_e32 v155, 0xbfb8aa3b, v125
	v_mul_f32_e32 v158, 0xbfb8aa3b, v126
	v_mul_f32_e32 v159, 0xbfb8aa3b, v127
	v_mul_f32_e32 v160, 0xbfb8aa3b, v120
	v_mul_f32_e32 v161, 0xbfb8aa3b, v121
	v_mul_f32_e32 v162, 0xbfb8aa3b, v122
	v_mul_f32_e32 v163, 0xbfb8aa3b, v123
	v_exp_f32_e32 v154, v154
	v_exp_f32_e32 v155, v155
	v_exp_f32_e32 v158, v158
	v_exp_f32_e32 v159, v159
	v_exp_f32_e32 v160, v160
	v_exp_f32_e32 v161, v161
	v_exp_f32_e32 v162, v162
	v_exp_f32_e32 v163, v163
	v_add_f32_e32 v154, 1.0, v154
	v_add_f32_e32 v155, 1.0, v155
	v_add_f32_e32 v158, 1.0, v158
	v_add_f32_e32 v159, 1.0, v159
	v_add_f32_e32 v160, 1.0, v160
	v_add_f32_e32 v161, 1.0, v161
	v_add_f32_e32 v162, 1.0, v162
	v_add_f32_e32 v163, 1.0, v163
	v_rcp_f32_e32 v154, v154
	v_rcp_f32_e32 v155, v155
	v_rcp_f32_e32 v158, v158
	v_rcp_f32_e32 v159, v159
	v_rcp_f32_e32 v160, v160
	v_rcp_f32_e32 v161, v161
	v_rcp_f32_e32 v162, v162
	v_rcp_f32_e32 v163, v163
	v_pk_mul_f32 v[124:125], v[124:125], v[154:155]
	v_pk_mul_f32 v[126:127], v[126:127], v[158:159]
	v_pk_mul_f32 v[120:121], v[120:121], v[160:161]
	v_pk_mul_f32 v[122:123], v[122:123], v[162:163]
	v_pk_mul_f32 v[112:113], v[112:113], v[124:125]
	v_pk_mul_f32 v[114:115], v[114:115], v[126:127]
	v_pk_mul_f32 v[118:119], v[118:119], v[152:153] op_sel_hi:[1,0]
	v_pk_mul_f32 v[116:117], v[116:117], v[152:153] op_sel_hi:[1,0]
	v_pk_mul_f32 v[108:109], v[108:109], v[120:121]
	v_pk_mul_f32 v[110:111], v[110:111], v[122:123]
	v_cvt_pk_bf16_f32 v112, v112, v113
	v_cvt_pk_bf16_f32 v113, v114, v115
	v_mul_f32_e32 v164, 0xbfb8aa3b, v116
	v_mul_f32_e32 v165, 0xbfb8aa3b, v117
	v_mul_f32_e32 v166, 0xbfb8aa3b, v118
	v_mul_f32_e32 v167, 0xbfb8aa3b, v119
	v_cvt_pk_bf16_f32 v114, v108, v109
	v_cvt_pk_bf16_f32 v111, v110, v111
	ds_bpermute_b32 v108, v149, v112
	ds_bpermute_b32 v109, v149, v113
	v_exp_f32_e32 v164, v164
	v_exp_f32_e32 v165, v165
	v_exp_f32_e32 v166, v166
	v_exp_f32_e32 v167, v167
	ds_bpermute_b32 v110, v149, v114
	ds_bpermute_b32 v111, v149, v111
	v_add_f32_e32 v164, 1.0, v164
	v_add_f32_e32 v113, 1.0, v165
	s_waitcnt lgkmcnt(0)
	global_store_dwordx2 v[156:157], v[108:109], off
	global_store_dwordx2 v[156:157], v[110:111], off offset:32
	v_add_f32_e32 v108, 1.0, v166
	v_add_f32_e32 v109, 1.0, v167
	v_rcp_f32_e32 v112, v164
	v_rcp_f32_e32 v113, v113
	v_rcp_f32_e32 v108, v108
	v_rcp_f32_e32 v109, v109
	v_pk_mul_f32 v[102:103], v[102:103], v[152:153] op_sel_hi:[1,0]
	v_pk_mul_f32 v[100:101], v[100:101], v[152:153] op_sel_hi:[1,0]
	v_pk_mul_f32 v[110:111], v[116:117], v[112:113]
	v_pk_mul_f32 v[108:109], v[118:119], v[108:109]
	v_pk_mul_f32 v[100:101], v[100:101], v[110:111]
	v_pk_mul_f32 v[102:103], v[102:103], v[108:109]
	v_cvt_pk_bf16_f32 v100, v100, v101
	v_cvt_pk_bf16_f32 v101, v102, v103
	v_pk_mul_f32 v[102:103], v[106:107], v[152:153] op_sel_hi:[1,0]
	v_pk_mul_f32 v[104:105], v[104:105], v[152:153] op_sel_hi:[1,0]
	v_mul_f32_e32 v108, 0xbfb8aa3b, v102
	v_mul_f32_e32 v106, 0xbfb8aa3b, v104
	v_mul_f32_e32 v107, 0xbfb8aa3b, v105
	v_mul_f32_e32 v109, 0xbfb8aa3b, v103
	v_exp_f32_e32 v106, v106
	v_exp_f32_e32 v107, v107
	v_exp_f32_e32 v108, v108
	v_exp_f32_e32 v109, v109
	v_add_f32_e32 v106, 1.0, v106
	v_add_f32_e32 v107, 1.0, v107
	v_add_f32_e32 v108, 1.0, v108
	v_add_f32_e32 v109, 1.0, v109
	v_rcp_f32_e32 v106, v106
	v_rcp_f32_e32 v107, v107
	v_rcp_f32_e32 v108, v108
	v_rcp_f32_e32 v109, v109
	v_pk_mul_f32 v[94:95], v[94:95], v[152:153] op_sel_hi:[1,0]
	v_pk_mul_f32 v[92:93], v[92:93], v[152:153] op_sel_hi:[1,0]
	v_pk_mul_f32 v[104:105], v[104:105], v[106:107]
	v_pk_mul_f32 v[102:103], v[102:103], v[108:109]
	v_pk_mul_f32 v[92:93], v[92:93], v[104:105]
	v_pk_mul_f32 v[94:95], v[94:95], v[102:103]
	ds_bpermute_b32 v100, v149, v100
	ds_bpermute_b32 v101, v149, v101
	v_cvt_pk_bf16_f32 v92, v92, v93
	v_cvt_pk_bf16_f32 v93, v94, v95
	ds_bpermute_b32 v92, v149, v92
	ds_bpermute_b32 v93, v149, v93
	v_mad_i64_i32 v[94:95], s[22:23], v153, s47, v[136:137]
	v_lshl_add_u64 v[94:95], v[94:95], 0, v[140:141]
	s_waitcnt lgkmcnt(2)
	global_store_dwordx2 v[94:95], v[100:101], off
	s_waitcnt lgkmcnt(0)
	global_store_dwordx2 v[94:95], v[92:93], off offset:32
	v_pk_mul_f32 v[92:93], v[98:99], v[150:151] op_sel_hi:[1,0]
	v_pk_mul_f32 v[94:95], v[96:97], v[150:151] op_sel_hi:[1,0]
	v_mul_f32_e32 v98, 0xbfb8aa3b, v92
	v_mul_f32_e32 v96, 0xbfb8aa3b, v94
	v_mul_f32_e32 v97, 0xbfb8aa3b, v95
	v_mul_f32_e32 v99, 0xbfb8aa3b, v93
	v_exp_f32_e32 v96, v96
	v_exp_f32_e32 v97, v97
	v_exp_f32_e32 v98, v98
	v_exp_f32_e32 v99, v99
	v_add_f32_e32 v96, 1.0, v96
	v_add_f32_e32 v97, 1.0, v97
	v_add_f32_e32 v98, 1.0, v98
	v_add_f32_e32 v99, 1.0, v99
	v_rcp_f32_e32 v96, v96
	v_rcp_f32_e32 v97, v97
	v_rcp_f32_e32 v98, v98
	v_rcp_f32_e32 v99, v99
	v_pk_mul_f32 v[86:87], v[86:87], v[150:151] op_sel_hi:[1,0]
	v_pk_mul_f32 v[84:85], v[84:85], v[150:151] op_sel_hi:[1,0]
	v_pk_mul_f32 v[94:95], v[94:95], v[96:97]
	v_pk_mul_f32 v[92:93], v[92:93], v[98:99]
	v_pk_mul_f32 v[84:85], v[84:85], v[94:95]
	v_pk_mul_f32 v[86:87], v[86:87], v[92:93]
	v_cvt_pk_bf16_f32 v84, v84, v85
	v_cvt_pk_bf16_f32 v85, v86, v87
	v_pk_mul_f32 v[86:87], v[90:91], v[150:151] op_sel_hi:[1,0]
	v_pk_mul_f32 v[88:89], v[88:89], v[150:151] op_sel_hi:[1,0]
	v_mul_f32_e32 v92, 0xbfb8aa3b, v86
	v_mul_f32_e32 v90, 0xbfb8aa3b, v88
	v_mul_f32_e32 v91, 0xbfb8aa3b, v89
	v_mul_f32_e32 v93, 0xbfb8aa3b, v87
	v_exp_f32_e32 v90, v90
	v_exp_f32_e32 v91, v91
	v_exp_f32_e32 v92, v92
	v_exp_f32_e32 v93, v93
	v_add_f32_e32 v90, 1.0, v90
	v_add_f32_e32 v91, 1.0, v91
	v_add_f32_e32 v92, 1.0, v92
	v_add_f32_e32 v93, 1.0, v93
	v_rcp_f32_e32 v90, v90
	v_rcp_f32_e32 v91, v91
	v_rcp_f32_e32 v92, v92
	v_rcp_f32_e32 v93, v93
	v_pk_mul_f32 v[78:79], v[78:79], v[150:151] op_sel_hi:[1,0]
	v_pk_mul_f32 v[76:77], v[76:77], v[150:151] op_sel_hi:[1,0]
	v_pk_mul_f32 v[88:89], v[88:89], v[90:91]
	v_pk_mul_f32 v[86:87], v[86:87], v[92:93]
	v_pk_mul_f32 v[76:77], v[76:77], v[88:89]
	v_pk_mul_f32 v[78:79], v[78:79], v[86:87]
	ds_bpermute_b32 v84, v149, v84
	ds_bpermute_b32 v85, v149, v85
	v_cvt_pk_bf16_f32 v76, v76, v77
	v_cvt_pk_bf16_f32 v77, v78, v79
	ds_bpermute_b32 v76, v149, v76
	ds_bpermute_b32 v77, v149, v77
	v_add_u32_e32 v100, 32, v151
	v_mad_i64_i32 v[78:79], s[22:23], v100, s47, v[136:137]
	v_lshl_add_u64 v[78:79], v[78:79], 0, v[140:141]
	s_waitcnt lgkmcnt(2)
	global_store_dwordx2 v[78:79], v[84:85], off
	s_waitcnt lgkmcnt(0)
	global_store_dwordx2 v[78:79], v[76:77], off offset:32
	v_pk_mul_f32 v[76:77], v[82:83], v[148:149] op_sel_hi:[1,0]
	v_pk_mul_f32 v[78:79], v[80:81], v[148:149] op_sel_hi:[1,0]
	v_mul_f32_e32 v82, 0xbfb8aa3b, v76
	v_mul_f32_e32 v80, 0xbfb8aa3b, v78
	v_mul_f32_e32 v81, 0xbfb8aa3b, v79
	v_mul_f32_e32 v83, 0xbfb8aa3b, v77
	v_exp_f32_e32 v80, v80
	v_exp_f32_e32 v81, v81
	v_exp_f32_e32 v82, v82
	v_exp_f32_e32 v83, v83
	v_add_f32_e32 v80, 1.0, v80
	v_add_f32_e32 v81, 1.0, v81
	v_add_f32_e32 v82, 1.0, v82
	v_add_f32_e32 v83, 1.0, v83
	v_rcp_f32_e32 v80, v80
	v_rcp_f32_e32 v81, v81
	v_rcp_f32_e32 v82, v82
	v_rcp_f32_e32 v83, v83
	v_pk_mul_f32 v[70:71], v[70:71], v[148:149] op_sel_hi:[1,0]
	v_pk_mul_f32 v[68:69], v[68:69], v[148:149] op_sel_hi:[1,0]
	v_pk_mul_f32 v[78:79], v[78:79], v[80:81]
	v_pk_mul_f32 v[76:77], v[76:77], v[82:83]
	v_pk_mul_f32 v[68:69], v[68:69], v[78:79]
	v_pk_mul_f32 v[70:71], v[70:71], v[76:77]
	v_cvt_pk_bf16_f32 v68, v68, v69
	v_cvt_pk_bf16_f32 v69, v70, v71
	v_pk_mul_f32 v[70:71], v[74:75], v[148:149] op_sel_hi:[1,0]
	v_pk_mul_f32 v[72:73], v[72:73], v[148:149] op_sel_hi:[1,0]
	v_mul_f32_e32 v76, 0xbfb8aa3b, v70
	v_mul_f32_e32 v74, 0xbfb8aa3b, v72
	v_mul_f32_e32 v75, 0xbfb8aa3b, v73
	v_mul_f32_e32 v77, 0xbfb8aa3b, v71
	v_exp_f32_e32 v74, v74
	v_exp_f32_e32 v75, v75
	v_exp_f32_e32 v76, v76
	v_exp_f32_e32 v77, v77
	v_add_f32_e32 v74, 1.0, v74
	v_add_f32_e32 v75, 1.0, v75
	v_add_f32_e32 v76, 1.0, v76
	v_add_f32_e32 v77, 1.0, v77
	v_rcp_f32_e32 v74, v74
	v_rcp_f32_e32 v75, v75
	v_rcp_f32_e32 v76, v76
	v_rcp_f32_e32 v77, v77
	v_pk_mul_f32 v[66:67], v[66:67], v[148:149] op_sel_hi:[1,0]
	v_pk_mul_f32 v[64:65], v[64:65], v[148:149] op_sel_hi:[1,0]
	v_pk_mul_f32 v[72:73], v[72:73], v[74:75]
	v_pk_mul_f32 v[70:71], v[70:71], v[76:77]
	v_pk_mul_f32 v[64:65], v[64:65], v[72:73]
	v_pk_mul_f32 v[66:67], v[66:67], v[70:71]
	ds_bpermute_b32 v68, v149, v68
	ds_bpermute_b32 v69, v149, v69
	v_cvt_pk_bf16_f32 v64, v64, v65
	v_cvt_pk_bf16_f32 v65, v66, v67
	ds_bpermute_b32 v64, v149, v64
	ds_bpermute_b32 v65, v149, v65
	v_add_u32_e32 v84, 48, v151
	v_mad_i64_i32 v[66:67], s[22:23], v84, s47, v[136:137]
	v_lshl_add_u64 v[66:67], v[66:67], 0, v[140:141]
	v_pk_mul_f32 v[60:61], v[60:61], v[146:147] op_sel_hi:[1,0]
	s_waitcnt lgkmcnt(2)
	global_store_dwordx2 v[66:67], v[68:69], off
	s_waitcnt lgkmcnt(0)
	global_store_dwordx2 v[66:67], v[64:65], off offset:32
	v_pk_mul_f32 v[62:63], v[62:63], v[146:147] op_sel_hi:[1,0]
	v_mul_f32_e32 v64, 0xbfb8aa3b, v60
	v_mul_f32_e32 v65, 0xbfb8aa3b, v61
	v_exp_f32_e32 v64, v64
	v_exp_f32_e32 v65, v65
	v_mul_f32_e32 v66, 0xbfb8aa3b, v62
	v_mul_f32_e32 v67, 0xbfb8aa3b, v63
	v_exp_f32_e32 v66, v66
	v_exp_f32_e32 v67, v67
	v_add_f32_e32 v64, 1.0, v64
	v_add_f32_e32 v65, 1.0, v65
	v_rcp_f32_e32 v64, v64
	v_rcp_f32_e32 v65, v65
	v_add_f32_e32 v66, 1.0, v66
	v_add_f32_e32 v67, 1.0, v67
	v_rcp_f32_e32 v66, v66
	v_rcp_f32_e32 v67, v67
	v_pk_mul_f32 v[52:53], v[52:53], v[146:147] op_sel_hi:[1,0]
	v_pk_mul_f32 v[60:61], v[60:61], v[64:65]
	v_pk_mul_f32 v[54:55], v[54:55], v[146:147] op_sel_hi:[1,0]
	v_pk_mul_f32 v[52:53], v[52:53], v[60:61]
	v_pk_mul_f32 v[60:61], v[62:63], v[66:67]
	v_cvt_pk_bf16_f32 v52, v52, v53
	v_pk_mul_f32 v[54:55], v[54:55], v[60:61]
	v_pk_mul_f32 v[56:57], v[56:57], v[146:147] op_sel_hi:[1,0]
	v_cvt_pk_bf16_f32 v53, v54, v55
	v_pk_mul_f32 v[54:55], v[58:59], v[146:147] op_sel_hi:[1,0]
	v_mul_f32_e32 v58, 0xbfb8aa3b, v56
	v_mul_f32_e32 v59, 0xbfb8aa3b, v57
	v_mul_f32_e32 v60, 0xbfb8aa3b, v54
	v_mul_f32_e32 v61, 0xbfb8aa3b, v55
	v_exp_f32_e32 v58, v58
	v_exp_f32_e32 v59, v59
	v_exp_f32_e32 v60, v60
	v_exp_f32_e32 v61, v61
	v_add_f32_e32 v58, 1.0, v58
	v_add_f32_e32 v59, 1.0, v59
	v_add_f32_e32 v60, 1.0, v60
	v_add_f32_e32 v61, 1.0, v61
	v_rcp_f32_e32 v58, v58
	v_rcp_f32_e32 v59, v59
	v_rcp_f32_e32 v60, v60
	v_rcp_f32_e32 v61, v61
	v_pk_mul_f32 v[46:47], v[46:47], v[146:147] op_sel_hi:[1,0]
	v_pk_mul_f32 v[44:45], v[44:45], v[146:147] op_sel_hi:[1,0]
	v_pk_mul_f32 v[56:57], v[56:57], v[58:59]
	v_pk_mul_f32 v[54:55], v[54:55], v[60:61]
	v_pk_mul_f32 v[44:45], v[44:45], v[56:57]
	v_pk_mul_f32 v[46:47], v[46:47], v[54:55]
	ds_bpermute_b32 v52, v149, v52
	ds_bpermute_b32 v53, v149, v53
	v_cvt_pk_bf16_f32 v44, v44, v45
	v_cvt_pk_bf16_f32 v45, v46, v47
	ds_bpermute_b32 v44, v149, v44
	ds_bpermute_b32 v45, v149, v45
	v_add_u32_e32 v68, 0x80, v151
	v_mad_i64_i32 v[46:47], s[22:23], v68, s47, v[136:137]
	v_lshl_add_u64 v[46:47], v[46:47], 0, v[140:141]
	s_waitcnt lgkmcnt(2)
	global_store_dwordx2 v[46:47], v[52:53], off
	s_waitcnt lgkmcnt(0)
	global_store_dwordx2 v[46:47], v[44:45], off offset:32
	v_pk_mul_f32 v[44:45], v[50:51], v[144:145] op_sel_hi:[1,0]
	v_pk_mul_f32 v[46:47], v[48:49], v[144:145] op_sel_hi:[1,0]
	v_mul_f32_e32 v50, 0xbfb8aa3b, v44
	v_mul_f32_e32 v48, 0xbfb8aa3b, v46
	v_mul_f32_e32 v49, 0xbfb8aa3b, v47
	v_mul_f32_e32 v51, 0xbfb8aa3b, v45
	v_exp_f32_e32 v48, v48
	v_exp_f32_e32 v49, v49
	v_exp_f32_e32 v50, v50
	v_exp_f32_e32 v51, v51
	v_add_f32_e32 v48, 1.0, v48
	v_add_f32_e32 v49, 1.0, v49
	v_add_f32_e32 v50, 1.0, v50
	v_add_f32_e32 v51, 1.0, v51
	v_rcp_f32_e32 v48, v48
	v_rcp_f32_e32 v49, v49
	v_rcp_f32_e32 v50, v50
	v_rcp_f32_e32 v51, v51
	v_pk_mul_f32 v[38:39], v[38:39], v[144:145] op_sel_hi:[1,0]
	v_pk_mul_f32 v[36:37], v[36:37], v[144:145] op_sel_hi:[1,0]
	v_pk_mul_f32 v[46:47], v[46:47], v[48:49]
	v_pk_mul_f32 v[44:45], v[44:45], v[50:51]
	v_pk_mul_f32 v[36:37], v[36:37], v[46:47]
	v_pk_mul_f32 v[38:39], v[38:39], v[44:45]
	v_cvt_pk_bf16_f32 v36, v36, v37
	v_cvt_pk_bf16_f32 v37, v38, v39
	v_pk_mul_f32 v[38:39], v[42:43], v[144:145] op_sel_hi:[1,0]
	v_pk_mul_f32 v[40:41], v[40:41], v[144:145] op_sel_hi:[1,0]
	v_mul_f32_e32 v44, 0xbfb8aa3b, v38
	v_mul_f32_e32 v42, 0xbfb8aa3b, v40
	v_mul_f32_e32 v43, 0xbfb8aa3b, v41
	v_mul_f32_e32 v45, 0xbfb8aa3b, v39
	v_exp_f32_e32 v42, v42
	v_exp_f32_e32 v43, v43
	v_exp_f32_e32 v44, v44
	v_exp_f32_e32 v45, v45
	v_add_f32_e32 v42, 1.0, v42
	v_add_f32_e32 v43, 1.0, v43
	v_add_f32_e32 v44, 1.0, v44
	v_add_f32_e32 v45, 1.0, v45
	v_rcp_f32_e32 v42, v42
	v_rcp_f32_e32 v43, v43
	v_rcp_f32_e32 v44, v44
	v_rcp_f32_e32 v45, v45
	v_pk_mul_f32 v[30:31], v[30:31], v[144:145] op_sel_hi:[1,0]
	v_pk_mul_f32 v[28:29], v[28:29], v[144:145] op_sel_hi:[1,0]
	v_pk_mul_f32 v[40:41], v[40:41], v[42:43]
	v_pk_mul_f32 v[38:39], v[38:39], v[44:45]
	v_pk_mul_f32 v[28:29], v[28:29], v[40:41]
	v_pk_mul_f32 v[30:31], v[30:31], v[38:39]
	ds_bpermute_b32 v36, v149, v36
	ds_bpermute_b32 v37, v149, v37
	v_cvt_pk_bf16_f32 v28, v28, v29
	v_cvt_pk_bf16_f32 v29, v30, v31
	ds_bpermute_b32 v28, v149, v28
	ds_bpermute_b32 v29, v149, v29
	v_add_u32_e32 v52, 0x90, v151
	v_mad_i64_i32 v[30:31], s[22:23], v52, s47, v[136:137]
	v_lshl_add_u64 v[30:31], v[30:31], 0, v[140:141]
	s_waitcnt lgkmcnt(2)
	global_store_dwordx2 v[30:31], v[36:37], off
	s_waitcnt lgkmcnt(0)
	global_store_dwordx2 v[30:31], v[28:29], off offset:32
	v_pk_mul_f32 v[28:29], v[34:35], v[142:143] op_sel_hi:[1,0]
	v_pk_mul_f32 v[30:31], v[32:33], v[142:143] op_sel_hi:[1,0]
	v_mul_f32_e32 v34, 0xbfb8aa3b, v28
	v_mul_f32_e32 v32, 0xbfb8aa3b, v30
	v_mul_f32_e32 v33, 0xbfb8aa3b, v31
	v_mul_f32_e32 v35, 0xbfb8aa3b, v29
	v_exp_f32_e32 v32, v32
	v_exp_f32_e32 v33, v33
	v_exp_f32_e32 v34, v34
	v_exp_f32_e32 v35, v35
	v_add_f32_e32 v32, 1.0, v32
	v_add_f32_e32 v33, 1.0, v33
	v_add_f32_e32 v34, 1.0, v34
	v_add_f32_e32 v35, 1.0, v35
	v_rcp_f32_e32 v32, v32
	v_rcp_f32_e32 v33, v33
	v_rcp_f32_e32 v34, v34
	v_rcp_f32_e32 v35, v35
	v_pk_mul_f32 v[22:23], v[22:23], v[142:143] op_sel_hi:[1,0]
	v_pk_mul_f32 v[20:21], v[20:21], v[142:143] op_sel_hi:[1,0]
	v_pk_mul_f32 v[30:31], v[30:31], v[32:33]
	v_pk_mul_f32 v[28:29], v[28:29], v[34:35]
	v_pk_mul_f32 v[20:21], v[20:21], v[30:31]
	v_pk_mul_f32 v[22:23], v[22:23], v[28:29]
	v_cvt_pk_bf16_f32 v20, v20, v21
	v_cvt_pk_bf16_f32 v21, v22, v23
	v_pk_mul_f32 v[22:23], v[26:27], v[142:143] op_sel_hi:[1,0]
	v_pk_mul_f32 v[24:25], v[24:25], v[142:143] op_sel_hi:[1,0]
	v_mul_f32_e32 v28, 0xbfb8aa3b, v22
	v_mul_f32_e32 v26, 0xbfb8aa3b, v24
	v_mul_f32_e32 v27, 0xbfb8aa3b, v25
	v_mul_f32_e32 v29, 0xbfb8aa3b, v23
	v_exp_f32_e32 v26, v26
	v_exp_f32_e32 v27, v27
	v_exp_f32_e32 v28, v28
	v_exp_f32_e32 v29, v29
	v_add_f32_e32 v26, 1.0, v26
	v_add_f32_e32 v27, 1.0, v27
	v_add_f32_e32 v28, 1.0, v28
	v_add_f32_e32 v29, 1.0, v29
	v_rcp_f32_e32 v26, v26
	v_rcp_f32_e32 v27, v27
	v_rcp_f32_e32 v28, v28
	v_rcp_f32_e32 v29, v29
	v_pk_mul_f32 v[14:15], v[14:15], v[142:143] op_sel_hi:[1,0]
	v_pk_mul_f32 v[12:13], v[12:13], v[142:143] op_sel_hi:[1,0]
	v_pk_mul_f32 v[24:25], v[24:25], v[26:27]
	v_pk_mul_f32 v[22:23], v[22:23], v[28:29]
	v_pk_mul_f32 v[12:13], v[12:13], v[24:25]
	v_pk_mul_f32 v[14:15], v[14:15], v[22:23]
	ds_bpermute_b32 v20, v149, v20
	ds_bpermute_b32 v21, v149, v21
	v_cvt_pk_bf16_f32 v12, v12, v13
	v_cvt_pk_bf16_f32 v13, v14, v15
	ds_bpermute_b32 v12, v149, v12
	ds_bpermute_b32 v13, v149, v13
	v_add_u32_e32 v36, 0xa0, v151
	v_mad_i64_i32 v[14:15], s[22:23], v36, s47, v[136:137]
	v_lshl_add_u64 v[14:15], v[14:15], 0, v[140:141]
	s_waitcnt lgkmcnt(2)
	global_store_dwordx2 v[14:15], v[20:21], off
	s_waitcnt lgkmcnt(0)
	global_store_dwordx2 v[14:15], v[12:13], off offset:32
	v_pk_mul_f32 v[12:13], v[18:19], v[138:139] op_sel_hi:[1,0]
	v_pk_mul_f32 v[14:15], v[16:17], v[138:139] op_sel_hi:[1,0]
	v_mul_f32_e32 v18, 0xbfb8aa3b, v12
	v_mul_f32_e32 v16, 0xbfb8aa3b, v14
	v_mul_f32_e32 v17, 0xbfb8aa3b, v15
	v_mul_f32_e32 v19, 0xbfb8aa3b, v13
	v_exp_f32_e32 v16, v16
	v_exp_f32_e32 v17, v17
	v_exp_f32_e32 v18, v18
	v_exp_f32_e32 v19, v19
	v_add_f32_e32 v16, 1.0, v16
	v_add_f32_e32 v17, 1.0, v17
	v_add_f32_e32 v18, 1.0, v18
	v_add_f32_e32 v19, 1.0, v19
	v_rcp_f32_e32 v16, v16
	v_rcp_f32_e32 v17, v17
	v_rcp_f32_e32 v18, v18
	v_rcp_f32_e32 v19, v19
	v_pk_mul_f32 v[6:7], v[6:7], v[138:139] op_sel_hi:[1,0]
	v_pk_mul_f32 v[4:5], v[4:5], v[138:139] op_sel_hi:[1,0]
	v_pk_mul_f32 v[14:15], v[14:15], v[16:17]
	v_pk_mul_f32 v[12:13], v[12:13], v[18:19]
	v_pk_mul_f32 v[4:5], v[4:5], v[14:15]
	v_pk_mul_f32 v[6:7], v[6:7], v[12:13]
	v_cvt_pk_bf16_f32 v4, v4, v5
	v_cvt_pk_bf16_f32 v5, v6, v7
	v_pk_mul_f32 v[6:7], v[10:11], v[138:139] op_sel_hi:[1,0]
	v_pk_mul_f32 v[8:9], v[8:9], v[138:139] op_sel_hi:[1,0]
	v_mul_f32_e32 v12, 0xbfb8aa3b, v6
	v_mul_f32_e32 v10, 0xbfb8aa3b, v8
	v_mul_f32_e32 v11, 0xbfb8aa3b, v9
	v_mul_f32_e32 v13, 0xbfb8aa3b, v7
	v_exp_f32_e32 v10, v10
	v_exp_f32_e32 v11, v11
	v_exp_f32_e32 v12, v12
	v_exp_f32_e32 v13, v13
	v_add_f32_e32 v10, 1.0, v10
	v_add_f32_e32 v11, 1.0, v11
	v_add_f32_e32 v12, 1.0, v12
	v_add_f32_e32 v13, 1.0, v13
	v_rcp_f32_e32 v10, v10
	v_rcp_f32_e32 v11, v11
	v_rcp_f32_e32 v12, v12
	v_rcp_f32_e32 v13, v13
	v_pk_mul_f32 v[2:3], v[2:3], v[138:139] op_sel_hi:[1,0]
	v_pk_mul_f32 v[0:1], v[0:1], v[138:139] op_sel_hi:[1,0]
	v_pk_mul_f32 v[8:9], v[8:9], v[10:11]
	v_pk_mul_f32 v[6:7], v[6:7], v[12:13]
	v_pk_mul_f32 v[0:1], v[0:1], v[8:9]
	v_pk_mul_f32 v[2:3], v[2:3], v[6:7]
	ds_bpermute_b32 v4, v149, v4
	ds_bpermute_b32 v5, v149, v5
	v_cvt_pk_bf16_f32 v0, v0, v1
	v_cvt_pk_bf16_f32 v1, v2, v3
	ds_bpermute_b32 v0, v149, v0
	ds_bpermute_b32 v1, v149, v1
	v_add_u32_e32 v20, 0xb0, v151
	v_mad_i64_i32 v[2:3], s[22:23], v20, s47, v[136:137]
	v_lshl_add_u64 v[2:3], v[2:3], 0, v[140:141]
	s_mov_b64 s[22:23], s[16:17]
	s_waitcnt lgkmcnt(2)
	global_store_dwordx2 v[2:3], v[4:5], off
	s_waitcnt lgkmcnt(0)
	global_store_dwordx2 v[2:3], v[0:1], off offset:32
	s_cbranch_vccz .LBB0_1164
	s_waitcnt vmcnt(0)
	s_cmpk_gt_u32 s28, 0xff
	s_cbranch_scc1 .LBB0_1171
	s_barrier

.LBB0_1258:
	ds_read_b128 v[128:131], v159
	ds_read_b128 v[132:135], v159 offset:1024
	ds_read_b128 v[136:139], v159 offset:2048
	ds_read_b128 v[150:153], v159 offset:3072
	s_add_i32 s54, s18, 2
	s_add_u32 s19, s16, 0xffea0080
	s_addc_u32 s20, s17, -1
	s_cmp_eq_u32 s13, s18
	s_cselect_b32 s18, s4, s52
	s_cselect_b32 s21, s15, s20
	s_cselect_b32 s20, s14, s19
	s_cselect_b32 s19, s5, s53

	s_add_i32 m0, s26, 0xc000
	ds_read_b128 v[154:157], v160
	ds_read_b128 v[162:165], v160 offset:1024
	ds_read_b128 v[172:175], v160 offset:2048
	ds_read_b128 v[176:179], v160 offset:3072
	ds_read_b128 v[180:183], v160 offset:4096
	ds_read_b128 v[184:187], v160 offset:5120
	ds_read_b128 v[188:191], v160 offset:6144

	global_load_lds_dwordx4 v146, s[16:17]
	s_add_i32 m0, s26, 0xe000
	ds_read_b128 v[192:195], v160 offset:7168

	global_load_lds_dwordx4 v148, s[16:17]
	s_waitcnt lgkmcnt(8)
	s_barrier
	s_waitcnt lgkmcnt(0)


	v_mfma_f32_16x16x32_bf16 v[124:127], v[128:131], v[154:157], v[124:127]
	v_mfma_f32_16x16x32_bf16 v[120:123], v[136:139], v[154:157], v[120:123]
	v_mfma_f32_16x16x32_bf16 v[116:119], v[128:131], v[172:175], v[116:119]
	v_mfma_f32_16x16x32_bf16 v[104:107], v[136:139], v[172:175], v[104:107]
	v_mfma_f32_16x16x32_bf16 v[96:99], v[128:131], v[180:183], v[96:99]
	v_mfma_f32_16x16x32_bf16 v[88:91], v[136:139], v[180:183], v[88:91]
	v_mfma_f32_16x16x32_bf16 v[80:83], v[128:131], v[188:191], v[80:83]
	v_mfma_f32_16x16x32_bf16 v[72:75], v[136:139], v[188:191], v[72:75]
	v_mfma_f32_16x16x32_bf16 v[124:127], v[132:135], v[162:165], v[124:127]
	v_mfma_f32_16x16x32_bf16 v[120:123], v[150:153], v[162:165], v[120:123]
	v_mfma_f32_16x16x32_bf16 v[116:119], v[132:135], v[176:179], v[116:119]
	v_mfma_f32_16x16x32_bf16 v[104:107], v[150:153], v[176:179], v[104:107]
	v_mfma_f32_16x16x32_bf16 v[96:99], v[132:135], v[184:187], v[96:99]
	v_mfma_f32_16x16x32_bf16 v[88:91], v[150:153], v[184:187], v[88:91]
	v_mfma_f32_16x16x32_bf16 v[80:83], v[132:135], v[192:195], v[80:83]
	v_mfma_f32_16x16x32_bf16 v[72:75], v[150:153], v[192:195], v[72:75]

	s_barrier
	s_add_i32 s55, s35, s25
	s_add_u32 s66, s18, s6
	s_addc_u32 s67, s19, s7
	s_mov_b32 m0, s55
	ds_read_b128 v[196:199], v161
	ds_read_b128 v[200:203], v161 offset:1024
	ds_read_b128 v[204:207], v161 offset:2048

	global_load_lds_dwordx4 v140, s[18:19]
	s_add_i32 m0, s55, 0x2000
	ds_read_b128 v[212:215], v161 offset:3072

	global_load_lds_dwordx4 v142, s[18:19]
	s_barrier
	s_waitcnt lgkmcnt(0)


	v_mfma_f32_16x16x32_bf16 v[112:115], v[196:199], v[154:157], v[112:115]
	v_mfma_f32_16x16x32_bf16 v[108:111], v[204:207], v[154:157], v[108:111]
	v_mfma_f32_16x16x32_bf16 v[100:103], v[196:199], v[172:175], v[100:103]
	v_mfma_f32_16x16x32_bf16 v[92:95], v[204:207], v[172:175], v[92:95]
	v_mfma_f32_16x16x32_bf16 v[84:87], v[196:199], v[180:183], v[84:87]
	v_mfma_f32_16x16x32_bf16 v[76:79], v[204:207], v[180:183], v[76:79]
	v_mfma_f32_16x16x32_bf16 v[68:71], v[196:199], v[188:191], v[68:71]
	v_mfma_f32_16x16x32_bf16 v[64:67], v[204:207], v[188:191], v[64:67]
	v_mfma_f32_16x16x32_bf16 v[112:115], v[200:203], v[162:165], v[112:115]
	v_mfma_f32_16x16x32_bf16 v[108:111], v[212:215], v[162:165], v[108:111]
	v_mfma_f32_16x16x32_bf16 v[100:103], v[200:203], v[176:179], v[100:103]
	v_mfma_f32_16x16x32_bf16 v[92:95], v[212:215], v[176:179], v[92:95]
	v_mfma_f32_16x16x32_bf16 v[84:87], v[200:203], v[184:187], v[84:87]
	v_mfma_f32_16x16x32_bf16 v[76:79], v[212:215], v[184:187], v[76:79]
	v_mfma_f32_16x16x32_bf16 v[68:71], v[200:203], v[192:195], v[68:71]
	v_mfma_f32_16x16x32_bf16 v[64:67], v[212:215], v[192:195], v[64:67]

	s_mov_b32 m0, s26
	s_add_u32 s68, s20, s6
	s_addc_u32 s69, s21, s7
	s_barrier
	ds_read_b128 v[154:157], v160 offset:16384
	ds_read_b128 v[162:165], v160 offset:17408
	ds_read_b128 v[172:175], v160 offset:18432
	ds_read_b128 v[176:179], v160 offset:19456
	ds_read_b128 v[180:183], v160 offset:20480
	ds_read_b128 v[184:187], v160 offset:21504
	ds_read_b128 v[188:191], v160 offset:22528

	global_load_lds_dwordx4 v140, s[20:21]
	s_mov_b32 m0, s27
	ds_read_b128 v[192:195], v160 offset:23552

	global_load_lds_dwordx4 v142, s[20:21]
	s_barrier
	s_waitcnt lgkmcnt(0)


	v_mfma_f32_16x16x32_bf16 v[60:63], v[128:131], v[154:157], v[60:63]
	v_mfma_f32_16x16x32_bf16 v[56:59], v[136:139], v[154:157], v[56:59]
	v_mfma_f32_16x16x32_bf16 v[52:55], v[128:131], v[172:175], v[52:55]
	v_mfma_f32_16x16x32_bf16 v[40:43], v[136:139], v[172:175], v[40:43]
	v_mfma_f32_16x16x32_bf16 v[36:39], v[128:131], v[180:183], v[36:39]
	v_mfma_f32_16x16x32_bf16 v[24:27], v[136:139], v[180:183], v[24:27]
	v_mfma_f32_16x16x32_bf16 v[20:23], v[128:131], v[188:191], v[20:23]
	v_mfma_f32_16x16x32_bf16 v[8:11], v[136:139], v[188:191], v[8:11]
	v_mfma_f32_16x16x32_bf16 v[60:63], v[132:135], v[162:165], v[60:63]
	v_mfma_f32_16x16x32_bf16 v[56:59], v[150:153], v[162:165], v[56:59]
	v_mfma_f32_16x16x32_bf16 v[52:55], v[132:135], v[176:179], v[52:55]
	v_mfma_f32_16x16x32_bf16 v[40:43], v[150:153], v[176:179], v[40:43]
	v_mfma_f32_16x16x32_bf16 v[36:39], v[132:135], v[184:187], v[36:39]
	v_mfma_f32_16x16x32_bf16 v[24:27], v[150:153], v[184:187], v[24:27]
	v_mfma_f32_16x16x32_bf16 v[20:23], v[132:135], v[192:195], v[20:23]
	v_mfma_f32_16x16x32_bf16 v[8:11], v[150:153], v[192:195], v[8:11]

	s_barrier
	s_add_i32 s55, s36, s25
	s_mov_b32 m0, s55
	s_add_u32 s56, s18, 0x160000
	s_addc_u32 s57, s19, 0


	global_load_lds_dwordx4 v140, s[56:57]
	s_add_i32 m0, s55, 0x2000
	s_nop 0

	global_load_lds_dwordx4 v142, s[56:57]
	s_waitcnt vmcnt(6)
	s_barrier

	v_mfma_f32_16x16x32_bf16 v[48:51], v[196:199], v[154:157], v[48:51]
	v_mfma_f32_16x16x32_bf16 v[44:47], v[204:207], v[154:157], v[44:47]
	v_mfma_f32_16x16x32_bf16 v[32:35], v[196:199], v[172:175], v[32:35]
	v_mfma_f32_16x16x32_bf16 v[28:31], v[204:207], v[172:175], v[28:31]
	v_mfma_f32_16x16x32_bf16 v[16:19], v[196:199], v[180:183], v[16:19]
	v_mfma_f32_16x16x32_bf16 v[12:15], v[204:207], v[180:183], v[12:15]
	v_mfma_f32_16x16x32_bf16 v[4:7], v[196:199], v[188:191], v[4:7]
	v_mfma_f32_16x16x32_bf16 v[0:3], v[204:207], v[188:191], v[0:3]
	v_mfma_f32_16x16x32_bf16 v[48:51], v[200:203], v[162:165], v[48:51]
	v_mfma_f32_16x16x32_bf16 v[44:47], v[212:215], v[162:165], v[44:47]
	v_mfma_f32_16x16x32_bf16 v[32:35], v[200:203], v[176:179], v[32:35]
	v_mfma_f32_16x16x32_bf16 v[28:31], v[212:215], v[176:179], v[28:31]
	v_mfma_f32_16x16x32_bf16 v[16:19], v[200:203], v[184:187], v[16:19]
	v_mfma_f32_16x16x32_bf16 v[12:15], v[212:215], v[184:187], v[12:15]
	v_mfma_f32_16x16x32_bf16 v[4:7], v[200:203], v[192:195], v[4:7]
	v_mfma_f32_16x16x32_bf16 v[0:3], v[212:215], v[192:195], v[0:3]

	s_add_i32 s55, 0, 0x18000
	v_add_u32_e32 v144, s55, v158
	s_barrier
	ds_read_b128 v[128:131], v144
	ds_read_b128 v[132:135], v144 offset:1024
	ds_read_b128 v[136:139], v144 offset:2048
	ds_read_b128 v[150:153], v144 offset:3072
	s_add_u32 s20, s20, 0x160000
	s_addc_u32 s21, s21, 0
	s_mov_b32 m0, s28

	ds_read_b128 v[154:157], v160 offset:32768
	ds_read_b128 v[162:165], v160 offset:33792
	ds_read_b128 v[172:175], v160 offset:34816
	ds_read_b128 v[176:179], v160 offset:35840
	ds_read_b128 v[180:183], v160 offset:36864
	ds_read_b128 v[184:187], v160 offset:37888
	ds_read_b128 v[188:191], v160 offset:38912

	global_load_lds_dwordx4 v140, s[20:21]
	s_mov_b32 m0, s29
	ds_read_b128 v[192:195], v160 offset:39936

	global_load_lds_dwordx4 v142, s[20:21]
	s_waitcnt lgkmcnt(8)
	s_barrier
	s_waitcnt lgkmcnt(0)


	v_mfma_f32_16x16x32_bf16 v[124:127], v[128:131], v[154:157], v[124:127]
	v_mfma_f32_16x16x32_bf16 v[120:123], v[136:139], v[154:157], v[120:123]
	v_mfma_f32_16x16x32_bf16 v[116:119], v[128:131], v[172:175], v[116:119]
	v_mfma_f32_16x16x32_bf16 v[104:107], v[136:139], v[172:175], v[104:107]
	v_mfma_f32_16x16x32_bf16 v[96:99], v[128:131], v[180:183], v[96:99]
	v_mfma_f32_16x16x32_bf16 v[88:91], v[136:139], v[180:183], v[88:91]
	v_mfma_f32_16x16x32_bf16 v[80:83], v[128:131], v[188:191], v[80:83]
	v_mfma_f32_16x16x32_bf16 v[72:75], v[136:139], v[188:191], v[72:75]
	v_mfma_f32_16x16x32_bf16 v[124:127], v[132:135], v[162:165], v[124:127]
	v_mfma_f32_16x16x32_bf16 v[120:123], v[150:153], v[162:165], v[120:123]
	v_mfma_f32_16x16x32_bf16 v[116:119], v[132:135], v[176:179], v[116:119]
	v_mfma_f32_16x16x32_bf16 v[104:107], v[150:153], v[176:179], v[104:107]
	v_mfma_f32_16x16x32_bf16 v[96:99], v[132:135], v[184:187], v[96:99]
	v_mfma_f32_16x16x32_bf16 v[88:91], v[150:153], v[184:187], v[88:91]
	v_mfma_f32_16x16x32_bf16 v[80:83], v[132:135], v[192:195], v[80:83]
	v_mfma_f32_16x16x32_bf16 v[72:75], v[150:153], v[192:195], v[72:75]

	s_barrier
	s_add_i32 s20, 0, 0x1c000
	s_add_i32 s21, s55, s25
	v_add_u32_e32 v144, s20, v158

	s_mov_b32 m0, s21
	ds_read_b128 v[196:199], v144
	ds_read_b128 v[200:203], v144 offset:1024
	ds_read_b128 v[204:207], v144 offset:2048

	global_load_lds_dwordx4 v140, s[66:67]
	s_add_i32 m0, s21, 0x2000
	ds_read_b128 v[212:215], v144 offset:3072

	global_load_lds_dwordx4 v142, s[66:67]
	s_barrier
	s_waitcnt lgkmcnt(0)


	v_mfma_f32_16x16x32_bf16 v[112:115], v[196:199], v[154:157], v[112:115]
	v_mfma_f32_16x16x32_bf16 v[108:111], v[204:207], v[154:157], v[108:111]
	v_mfma_f32_16x16x32_bf16 v[100:103], v[196:199], v[172:175], v[100:103]
	v_mfma_f32_16x16x32_bf16 v[92:95], v[204:207], v[172:175], v[92:95]
	v_mfma_f32_16x16x32_bf16 v[84:87], v[196:199], v[180:183], v[84:87]
	v_mfma_f32_16x16x32_bf16 v[76:79], v[204:207], v[180:183], v[76:79]
	v_mfma_f32_16x16x32_bf16 v[68:71], v[196:199], v[188:191], v[68:71]
	v_mfma_f32_16x16x32_bf16 v[64:67], v[204:207], v[188:191], v[64:67]
	v_mfma_f32_16x16x32_bf16 v[112:115], v[200:203], v[162:165], v[112:115]
	v_mfma_f32_16x16x32_bf16 v[108:111], v[212:215], v[162:165], v[108:111]
	v_mfma_f32_16x16x32_bf16 v[100:103], v[200:203], v[176:179], v[100:103]
	v_mfma_f32_16x16x32_bf16 v[92:95], v[212:215], v[176:179], v[92:95]
	v_mfma_f32_16x16x32_bf16 v[84:87], v[200:203], v[184:187], v[84:87]
	v_mfma_f32_16x16x32_bf16 v[76:79], v[212:215], v[184:187], v[76:79]
	v_mfma_f32_16x16x32_bf16 v[68:71], v[200:203], v[192:195], v[68:71]
	v_mfma_f32_16x16x32_bf16 v[64:67], v[212:215], v[192:195], v[64:67]

	s_mov_b32 m0, s33

	s_barrier
	ds_read_b128 v[154:157], v160 offset:49152
	ds_read_b128 v[162:165], v160 offset:50176
	ds_read_b128 v[172:175], v160 offset:51200
	ds_read_b128 v[176:179], v160 offset:52224
	ds_read_b128 v[180:183], v160 offset:53248
	ds_read_b128 v[184:187], v160 offset:54272
	ds_read_b128 v[188:191], v160 offset:55296

	global_load_lds_dwordx4 v140, s[68:69]
	s_mov_b32 m0, s34
	ds_read_b128 v[192:195], v160 offset:56320

	global_load_lds_dwordx4 v142, s[68:69]
	s_barrier
	s_waitcnt lgkmcnt(0)


	v_mfma_f32_16x16x32_bf16 v[60:63], v[128:131], v[154:157], v[60:63]
	v_mfma_f32_16x16x32_bf16 v[56:59], v[136:139], v[154:157], v[56:59]
	v_mfma_f32_16x16x32_bf16 v[52:55], v[128:131], v[172:175], v[52:55]
	v_mfma_f32_16x16x32_bf16 v[40:43], v[136:139], v[172:175], v[40:43]
	v_mfma_f32_16x16x32_bf16 v[36:39], v[128:131], v[180:183], v[36:39]
	v_mfma_f32_16x16x32_bf16 v[24:27], v[136:139], v[180:183], v[24:27]
	v_mfma_f32_16x16x32_bf16 v[20:23], v[128:131], v[188:191], v[20:23]
	v_mfma_f32_16x16x32_bf16 v[8:11], v[136:139], v[188:191], v[8:11]
	v_mfma_f32_16x16x32_bf16 v[60:63], v[132:135], v[162:165], v[60:63]
	v_mfma_f32_16x16x32_bf16 v[56:59], v[150:153], v[162:165], v[56:59]
	v_mfma_f32_16x16x32_bf16 v[52:55], v[132:135], v[176:179], v[52:55]
	v_mfma_f32_16x16x32_bf16 v[40:43], v[150:153], v[176:179], v[40:43]
	v_mfma_f32_16x16x32_bf16 v[36:39], v[132:135], v[184:187], v[36:39]
	v_mfma_f32_16x16x32_bf16 v[24:27], v[150:153], v[184:187], v[24:27]
	v_mfma_f32_16x16x32_bf16 v[20:23], v[132:135], v[192:195], v[20:23]
	v_mfma_f32_16x16x32_bf16 v[8:11], v[150:153], v[192:195], v[8:11]

	s_barrier
	s_add_i32 s20, s20, s25
	s_mov_b32 m0, s20
	s_add_u32 s18, s18, 0x160080
	s_addc_u32 s19, s19, 0


	global_load_lds_dwordx4 v140, s[18:19]
	s_add_i32 m0, s20, 0x2000
	s_nop 0

	global_load_lds_dwordx4 v142, s[18:19]
	s_waitcnt vmcnt(6)
	s_barrier

	v_mfma_f32_16x16x32_bf16 v[48:51], v[196:199], v[154:157], v[48:51]
	v_mfma_f32_16x16x32_bf16 v[44:47], v[204:207], v[154:157], v[44:47]
	v_mfma_f32_16x16x32_bf16 v[32:35], v[196:199], v[172:175], v[32:35]
	v_mfma_f32_16x16x32_bf16 v[28:31], v[204:207], v[172:175], v[28:31]
	v_mfma_f32_16x16x32_bf16 v[16:19], v[196:199], v[180:183], v[16:19]
	v_mfma_f32_16x16x32_bf16 v[12:15], v[204:207], v[180:183], v[12:15]
	v_mfma_f32_16x16x32_bf16 v[4:7], v[196:199], v[188:191], v[4:7]
	v_mfma_f32_16x16x32_bf16 v[0:3], v[204:207], v[188:191], v[0:3]
	v_mfma_f32_16x16x32_bf16 v[48:51], v[200:203], v[162:165], v[48:51]
	v_mfma_f32_16x16x32_bf16 v[44:47], v[212:215], v[162:165], v[44:47]
	v_mfma_f32_16x16x32_bf16 v[32:35], v[200:203], v[176:179], v[32:35]
	v_mfma_f32_16x16x32_bf16 v[28:31], v[212:215], v[176:179], v[28:31]
	v_mfma_f32_16x16x32_bf16 v[16:19], v[200:203], v[184:187], v[16:19]
	v_mfma_f32_16x16x32_bf16 v[12:15], v[212:215], v[184:187], v[12:15]
	v_mfma_f32_16x16x32_bf16 v[4:7], v[200:203], v[192:195], v[4:7]
	v_mfma_f32_16x16x32_bf16 v[0:3], v[212:215], v[192:195], v[0:3]

	s_add_u32 s16, s16, 0x100
	s_addc_u32 s17, s17, 0
	s_add_u32 s52, s52, 0x100
	s_addc_u32 s53, s53, 0
	s_cmp_ge_i32 s54, s51
	s_mov_b32 s18, s54
	s_barrier
	s_cbranch_scc0 .LBB0_1258
	v_mov_b32_e32 v128, v210
	v_mov_b32_e32 v129, v169
	s_mov_b64 s[16:17], -1
	v_lshl_add_u32 v128, v128, 4, v129
	v_ashrrev_i32_e32 v150, 2, v128
	v_and_b32_e32 v129, 3, v129
	v_and_b32_e32 v128, -4, v128
	v_lshl_add_u32 v162, v129, 6, v128
	s_cmp_lt_i32 s2, 0
	v_lshlrev_b32_e32 v144, 4, v129
	s_cbranch_scc0 .LBB0_1261
	s_lshl_b32 s13, s50, 8
	s_add_i32 s13, s13, s30
	v_add_u32_e32 v128, s13, v150
	v_ashrrev_i32_e32 v129, 31, v128
	v_readlane_b32 s52, v254, 22
	v_lshlrev_b64 v[128:129], 13, v[128:129]
	v_readlane_b32 s66, v254, 36
	v_readlane_b32 s67, v254, 37
	s_lshl_b32 s16, s49, 8
	s_ashr_i32 s17, s16, 31
	v_lshl_add_u64 v[128:129], s[66:67], 0, v[128:129]
	v_lshl_add_u64 v[128:129], s[16:17], 2, v[128:129]
	s_lshl_b32 s16, s31, 2
	s_mov_b32 s17, s3
	v_lshl_add_u64 v[128:129], v[128:129], 0, s[16:17]
	v_lshl_add_u64 v[152:153], v[128:129], 0, v[144:145]
	global_load_dwordx4 v[164:167], v[152:153], off
	global_load_dwordx4 v[172:175], v[152:153], off offset:64
	global_load_dwordx4 v[176:179], v[152:153], off offset:512
	global_load_dwordx4 v[180:183], v[152:153], off offset:576
	v_add_co_u32_e32 v136, vcc, s37, v152
	ds_bpermute_b32 v138, v162, v124
	s_nop 0
	v_addc_co_u32_e32 v137, vcc, 0, v153, vcc
	global_load_dwordx4 v[184:187], v[136:137], off
	global_load_dwordx4 v[188:191], v[136:137], off offset:64
	global_load_dwordx4 v[192:195], v[136:137], off offset:512
	global_load_dwordx4 v[132:135], v[136:137], off offset:576
	v_add_co_u32_e32 v208, vcc, s38, v152
	ds_bpermute_b32 v139, v162, v125
	s_nop 0
	v_addc_co_u32_e32 v209, vcc, 0, v153, vcc
	global_load_dwordx4 v[196:199], v[208:209], off
	global_load_dwordx4 v[200:203], v[208:209], off offset:64
	global_load_dwordx4 v[204:207], v[208:209], off offset:512
	global_load_dwordx4 v[212:215], v[208:209], off offset:576
	v_add_co_u32_e32 v154, vcc, s39, v152
	ds_bpermute_b32 v156, v162, v126
	s_nop 0
	v_addc_co_u32_e32 v155, vcc, 0, v153, vcc
	global_load_dwordx4 v[216:219], v[154:155], off
	global_load_dwordx4 v[220:223], v[154:155], off offset:64
	global_load_dwordx4 v[224:227], v[154:155], off offset:512
	global_load_dwordx4 v[128:131], v[154:155], off offset:576
	ds_bpermute_b32 v157, v162, v127
	ds_bpermute_b32 v228, v162, v120
	ds_bpermute_b32 v229, v162, v121
	ds_bpermute_b32 v230, v162, v122
	ds_bpermute_b32 v231, v162, v123
	ds_bpermute_b32 v232, v162, v112
	ds_bpermute_b32 v233, v162, v113
	ds_bpermute_b32 v234, v162, v114
	ds_bpermute_b32 v235, v162, v115
	ds_bpermute_b32 v236, v162, v108
	ds_bpermute_b32 v237, v162, v109
	ds_bpermute_b32 v238, v162, v110
	ds_bpermute_b32 v239, v162, v111
	ds_bpermute_b32 v240, v162, v116
	ds_bpermute_b32 v241, v162, v117
	ds_bpermute_b32 v242, v162, v118
	ds_bpermute_b32 v243, v162, v119
	ds_bpermute_b32 v244, v162, v104
	ds_bpermute_b32 v245, v162, v105
	ds_bpermute_b32 v246, v162, v106
	ds_bpermute_b32 v247, v162, v107
	ds_bpermute_b32 v248, v162, v100
	ds_bpermute_b32 v249, v162, v101
	ds_bpermute_b32 v250, v162, v102
	ds_bpermute_b32 v251, v162, v103
	ds_bpermute_b32 v252, v162, v94
	ds_bpermute_b32 v253, v162, v95
	v_readlane_b32 s53, v254, 23
	v_readlane_b32 s54, v254, 24
	v_readlane_b32 s55, v254, 25
	v_readlane_b32 s56, v254, 26
	v_readlane_b32 s57, v254, 27
	v_readlane_b32 s58, v254, 28
	v_readlane_b32 s59, v254, 29
	v_readlane_b32 s60, v254, 30
	v_readlane_b32 s61, v254, 31
	v_readlane_b32 s62, v254, 32
	v_readlane_b32 s63, v254, 33
	v_readlane_b32 s64, v254, 34
	v_readlane_b32 s65, v254, 35
	s_mov_b64 s[16:17], 0
	s_waitcnt vmcnt(0) lgkmcnt(0)
	v_pk_add_f32 v[164:165], v[164:165], v[138:139]
	ds_bpermute_b32 v138, v162, v92
	ds_bpermute_b32 v139, v162, v93
	v_pk_add_f32 v[166:167], v[166:167], v[156:157]
	v_pk_add_f32 v[172:173], v[172:173], v[228:229]
	v_pk_add_f32 v[174:175], v[174:175], v[230:231]
	v_pk_add_f32 v[178:179], v[178:179], v[234:235]
	v_pk_add_f32 v[176:177], v[176:177], v[232:233]
	v_pk_add_f32 v[182:183], v[182:183], v[238:239]
	v_pk_add_f32 v[180:181], v[180:181], v[236:237]
	global_store_dwordx4 v[152:153], v[164:167], off
	global_store_dwordx4 v[152:153], v[172:175], off offset:64
	global_store_dwordx4 v[152:153], v[176:179], off offset:512
	global_store_dwordx4 v[152:153], v[180:183], off offset:576
	v_pk_add_f32 v[166:167], v[186:187], v[242:243]
	v_pk_add_f32 v[164:165], v[184:185], v[240:241]
	v_pk_add_f32 v[172:173], v[188:189], v[244:245]
	v_add_co_u32_e32 v156, vcc, s40, v152
	v_pk_add_f32 v[174:175], v[190:191], v[246:247]
	v_pk_add_f32 v[178:179], v[194:195], v[250:251]
	v_pk_add_f32 v[176:177], v[192:193], v[248:249]
	global_store_dwordx4 v[136:137], v[164:167], off
	global_store_dwordx4 v[136:137], v[172:175], off offset:64
	global_store_dwordx4 v[136:137], v[176:179], off offset:512
	v_addc_co_u32_e32 v157, vcc, 0, v153, vcc
	ds_bpermute_b32 v172, v162, v98
	ds_bpermute_b32 v173, v162, v99
	v_pk_add_f32 v[134:135], v[134:135], v[252:253]
	global_load_dwordx4 v[164:167], v[156:157], off
	s_waitcnt lgkmcnt(2)
	v_pk_add_f32 v[132:133], v[132:133], v[138:139]
	global_store_dwordx4 v[136:137], v[132:135], off offset:576
	ds_bpermute_b32 v132, v162, v96
	ds_bpermute_b32 v133, v162, v97
	ds_bpermute_b32 v136, v162, v90
	ds_bpermute_b32 v137, v162, v91
	ds_bpermute_b32 v138, v162, v88
	ds_bpermute_b32 v139, v162, v89
	s_waitcnt lgkmcnt(6)
	v_pk_add_f32 v[134:135], v[198:199], v[172:173]
	global_load_dwordx4 v[172:175], v[156:157], off offset:64
	s_waitcnt lgkmcnt(4)
	v_pk_add_f32 v[132:133], v[196:197], v[132:133]
	global_store_dwordx4 v[208:209], v[132:135], off
	ds_bpermute_b32 v180, v162, v76
	ds_bpermute_b32 v182, v162, v78
	s_waitcnt lgkmcnt(4)
	v_pk_add_f32 v[134:135], v[202:203], v[136:137]
	ds_bpermute_b32 v136, v162, v86
	ds_bpermute_b32 v137, v162, v87
	s_waitcnt lgkmcnt(4)
	v_pk_add_f32 v[132:133], v[200:201], v[138:139]
	ds_bpermute_b32 v138, v162, v84
	ds_bpermute_b32 v139, v162, v85
	global_store_dwordx4 v[208:209], v[132:135], off offset:64
	global_load_dwordx4 v[132:135], v[156:157], off offset:512
	s_waitcnt lgkmcnt(2)
	v_pk_add_f32 v[178:179], v[206:207], v[136:137]
	ds_bpermute_b32 v183, v162, v79
	s_waitcnt lgkmcnt(1)
	v_pk_add_f32 v[176:177], v[204:205], v[138:139]
	global_load_dwordx4 v[136:139], v[156:157], off offset:576
	ds_bpermute_b32 v181, v162, v77
	global_store_dwordx4 v[208:209], v[176:179], off offset:512
	v_add_co_u32_e32 v204, vcc, s41, v152
	s_waitcnt lgkmcnt(1)
	v_pk_add_f32 v[178:179], v[214:215], v[182:183]
	s_waitcnt lgkmcnt(0)
	v_pk_add_f32 v[176:177], v[212:213], v[180:181]
	ds_bpermute_b32 v180, v162, v80
	ds_bpermute_b32 v181, v162, v81
	ds_bpermute_b32 v182, v162, v82
	ds_bpermute_b32 v183, v162, v83
	v_addc_co_u32_e32 v205, vcc, 0, v153, vcc
	global_store_dwordx4 v[208:209], v[176:179], off offset:576
	global_load_dwordx4 v[176:179], v[204:205], off
	s_waitcnt lgkmcnt(0)
	v_pk_add_f32 v[182:183], v[218:219], v[182:183]
	global_load_dwordx4 v[184:187], v[204:205], off offset:64
	v_pk_add_f32 v[180:181], v[216:217], v[180:181]
	ds_bpermute_b32 v188, v162, v74
	ds_bpermute_b32 v189, v162, v75
	global_store_dwordx4 v[154:155], v[180:183], off
	ds_bpermute_b32 v180, v162, v72
	ds_bpermute_b32 v181, v162, v73
	ds_bpermute_b32 v192, v162, v68
	s_waitcnt lgkmcnt(3)
	v_pk_add_f32 v[182:183], v[222:223], v[188:189]
	global_load_dwordx4 v[188:191], v[204:205], off offset:512
	ds_bpermute_b32 v193, v162, v69
	s_waitcnt lgkmcnt(2)
	v_pk_add_f32 v[180:181], v[220:221], v[180:181]
	ds_bpermute_b32 v194, v162, v70
	ds_bpermute_b32 v195, v162, v71
	global_store_dwordx4 v[154:155], v[180:183], off offset:64
	global_load_dwordx4 v[180:183], v[204:205], off offset:576
	ds_bpermute_b32 v200, v162, v64
	ds_bpermute_b32 v196, v162, v66
	ds_bpermute_b32 v197, v162, v67
	ds_bpermute_b32 v201, v162, v65
	v_add_co_u32_e32 v206, vcc, s42, v152
	s_waitcnt lgkmcnt(4)
	v_pk_add_f32 v[194:195], v[226:227], v[194:195]
	v_pk_add_f32 v[192:193], v[224:225], v[192:193]
	v_addc_co_u32_e32 v207, vcc, 0, v153, vcc
	global_store_dwordx4 v[154:155], v[192:195], off offset:512
	global_load_dwordx4 v[192:195], v[206:207], off
	s_waitcnt lgkmcnt(1)
	v_pk_add_f32 v[130:131], v[130:131], v[196:197]
	s_waitcnt lgkmcnt(0)
	v_pk_add_f32 v[128:129], v[128:129], v[200:201]
	global_load_dwordx4 v[196:199], v[206:207], off offset:64
	ds_bpermute_b32 v202, v162, v62
	ds_bpermute_b32 v203, v162, v63
	global_store_dwordx4 v[154:155], v[128:131], off offset:576
	ds_bpermute_b32 v128, v162, v60
	ds_bpermute_b32 v129, v162, v61
	ds_bpermute_b32 v208, v162, v58
	ds_bpermute_b32 v209, v162, v59
	s_waitcnt vmcnt(18) lgkmcnt(4)
	v_pk_add_f32 v[130:131], v[166:167], v[202:203]
	ds_bpermute_b32 v154, v162, v56
	global_load_dwordx4 v[200:203], v[206:207], off offset:512
	ds_bpermute_b32 v155, v162, v57
	s_waitcnt lgkmcnt(4)
	v_pk_add_f32 v[128:129], v[164:165], v[128:129]
	global_load_dwordx4 v[164:167], v[206:207], off offset:576
	ds_bpermute_b32 v212, v162, v44
	global_store_dwordx4 v[156:157], v[128:131], off
	ds_bpermute_b32 v214, v162, v46
	ds_bpermute_b32 v215, v162, v47
	s_waitcnt vmcnt(19) lgkmcnt(5)
	v_pk_add_f32 v[130:131], v[174:175], v[208:209]
	v_add_co_u32_e32 v208, vcc, s43, v152
	s_waitcnt lgkmcnt(3)
	v_pk_add_f32 v[128:129], v[172:173], v[154:155]
	v_addc_co_u32_e32 v209, vcc, 0, v153, vcc
	global_store_dwordx4 v[156:157], v[128:131], off offset:64
	ds_bpermute_b32 v172, v162, v48
	ds_bpermute_b32 v173, v162, v49
	global_load_dwordx4 v[128:131], v[208:209], off
	global_load_dwordx4 v[152:155], v[208:209], off offset:64
	ds_bpermute_b32 v174, v162, v50
	ds_bpermute_b32 v175, v162, v51
	ds_bpermute_b32 v213, v162, v45
	s_waitcnt vmcnt(19) lgkmcnt(3)
	v_pk_add_f32 v[132:133], v[132:133], v[172:173]
	ds_bpermute_b32 v172, v162, v54
	ds_bpermute_b32 v173, v162, v55
	s_waitcnt lgkmcnt(3)
	v_pk_add_f32 v[134:135], v[134:135], v[174:175]
	global_store_dwordx4 v[156:157], v[132:135], off offset:512
	s_waitcnt vmcnt(16) lgkmcnt(0)
	v_pk_add_f32 v[174:175], v[178:179], v[172:173]
	v_pk_add_f32 v[134:135], v[138:139], v[214:215]
	v_pk_add_f32 v[132:133], v[136:137], v[212:213]
	global_store_dwordx4 v[156:157], v[132:135], off offset:576
	global_load_dwordx4 v[132:135], v[208:209], off offset:512
	ds_bpermute_b32 v156, v162, v52
	global_load_dwordx4 v[136:139], v[208:209], off offset:576
	ds_bpermute_b32 v157, v162, v53
	ds_bpermute_b32 v212, v162, v40
	ds_bpermute_b32 v214, v162, v42
	ds_bpermute_b32 v215, v162, v43
	ds_bpermute_b32 v213, v162, v41
	s_waitcnt lgkmcnt(4)
	v_pk_add_f32 v[172:173], v[176:177], v[156:157]
	global_store_dwordx4 v[204:205], v[172:175], off
	ds_bpermute_b32 v156, v162, v32
	ds_bpermute_b32 v157, v162, v33
	s_waitcnt vmcnt(19) lgkmcnt(3)
	v_pk_add_f32 v[174:175], v[186:187], v[214:215]
	s_waitcnt lgkmcnt(2)
	v_pk_add_f32 v[172:173], v[184:185], v[212:213]
	global_store_dwordx4 v[204:205], v[172:175], off offset:64
	ds_bpermute_b32 v172, v162, v34
	ds_bpermute_b32 v173, v162, v35
	ds_bpermute_b32 v176, v162, v28
	ds_bpermute_b32 v178, v162, v30
	ds_bpermute_b32 v179, v162, v31
	ds_bpermute_b32 v177, v162, v29
	s_waitcnt vmcnt(18) lgkmcnt(4)
	v_pk_add_f32 v[174:175], v[190:191], v[172:173]
	v_pk_add_f32 v[172:173], v[188:189], v[156:157]
	global_store_dwordx4 v[204:205], v[172:175], off offset:512
	ds_bpermute_b32 v156, v162, v36
	ds_bpermute_b32 v157, v162, v37
	s_waitcnt vmcnt(17) lgkmcnt(3)
	v_pk_add_f32 v[174:175], v[182:183], v[178:179]
	s_waitcnt lgkmcnt(2)
	v_pk_add_f32 v[172:173], v[180:181], v[176:177]
	global_store_dwordx4 v[204:205], v[172:175], off offset:576
	ds_bpermute_b32 v172, v162, v38
	ds_bpermute_b32 v173, v162, v39
	ds_bpermute_b32 v176, v162, v24
	ds_bpermute_b32 v178, v162, v26
	ds_bpermute_b32 v179, v162, v27
	ds_bpermute_b32 v177, v162, v25
	s_waitcnt vmcnt(16) lgkmcnt(4)
	v_pk_add_f32 v[174:175], v[194:195], v[172:173]
	v_pk_add_f32 v[172:173], v[192:193], v[156:157]
	global_store_dwordx4 v[206:207], v[172:175], off
	ds_bpermute_b32 v156, v162, v16
	ds_bpermute_b32 v157, v162, v17
	s_waitcnt vmcnt(16) lgkmcnt(3)
	v_pk_add_f32 v[174:175], v[198:199], v[178:179]
	s_waitcnt lgkmcnt(2)
	v_pk_add_f32 v[172:173], v[196:197], v[176:177]
	ds_bpermute_b32 v176, v162, v12
	ds_bpermute_b32 v178, v162, v14
	ds_bpermute_b32 v179, v162, v15
	ds_bpermute_b32 v177, v162, v13
	global_store_dwordx4 v[206:207], v[172:175], off offset:64
	ds_bpermute_b32 v172, v162, v18
	ds_bpermute_b32 v173, v162, v19
	s_waitcnt vmcnt(14) lgkmcnt(3)
	v_pk_add_f32 v[166:167], v[166:167], v[178:179]
	s_waitcnt lgkmcnt(2)
	v_pk_add_f32 v[164:165], v[164:165], v[176:177]
	global_store_dwordx4 v[206:207], v[164:167], off offset:576
	ds_bpermute_b32 v164, v162, v22
	s_waitcnt lgkmcnt(1)
	v_pk_add_f32 v[174:175], v[202:203], v[172:173]
	v_pk_add_f32 v[172:173], v[200:201], v[156:157]
	ds_bpermute_b32 v156, v162, v20
	ds_bpermute_b32 v157, v162, v21
	ds_bpermute_b32 v165, v162, v23
	global_store_dwordx4 v[206:207], v[172:175], off offset:512
	ds_bpermute_b32 v166, v162, v8
	ds_bpermute_b32 v172, v162, v10
	ds_bpermute_b32 v173, v162, v11
	ds_bpermute_b32 v167, v162, v9
	s_waitcnt vmcnt(13) lgkmcnt(4)
	v_pk_add_f32 v[130:131], v[130:131], v[164:165]
	v_pk_add_f32 v[128:129], v[128:129], v[156:157]
	global_store_dwordx4 v[208:209], v[128:131], off
	s_waitcnt vmcnt(13) lgkmcnt(1)
	s_nop 0
	v_pk_add_f32 v[130:131], v[154:155], v[172:173]
	s_waitcnt lgkmcnt(0)
	v_pk_add_f32 v[128:129], v[152:153], v[166:167]
	global_store_dwordx4 v[208:209], v[128:131], off offset:64
	ds_bpermute_b32 v128, v162, v4
	ds_bpermute_b32 v129, v162, v5
	ds_bpermute_b32 v130, v162, v6
	ds_bpermute_b32 v131, v162, v7
	ds_bpermute_b32 v152, v162, v0
	ds_bpermute_b32 v154, v162, v2
	ds_bpermute_b32 v155, v162, v3
	ds_bpermute_b32 v153, v162, v1
	s_waitcnt vmcnt(11) lgkmcnt(4)
	v_pk_add_f32 v[130:131], v[134:135], v[130:131]
	v_pk_add_f32 v[128:129], v[132:133], v[128:129]
	global_store_dwordx4 v[208:209], v[128:131], off offset:512
	s_waitcnt vmcnt(11) lgkmcnt(1)
	s_nop 0
	v_pk_add_f32 v[130:131], v[138:139], v[154:155]
	s_waitcnt lgkmcnt(0)
	v_pk_add_f32 v[128:129], v[136:137], v[152:153]
	global_store_dwordx4 v[208:209], v[128:131], off offset:576
